# GEMM tiles: first K-iteration peeled with zero C operand on first-touch MFMAs; the 128 accumulator zero-init v_mov per tile removed
# speedup vs baseline: 1.0101x; 1.0101x over previous
.LBB0_215:
	s_ashr_i32 s43, s42, 31
	s_lshl_b64 s[28:29], s[42:43], 20
	s_add_u32 s44, s68, s28
	s_addc_u32 s45, s69, s29
	s_and_b64 s[28:29], s[38:39], exec
	s_cselect_b32 s43, s45, s51
	s_cselect_b32 s84, s44, s50
	s_ashr_i32 s41, s40, 31
	s_lshl_b64 s[28:29], s[40:41], 20
	v_readlane_b32 s41, v255, 6
	s_add_u32 s46, s41, s28
	v_readlane_b32 s28, v255, 7
	s_addc_u32 s47, s28, s29
	s_and_b64 s[28:29], s[38:39], exec
	s_cselect_b32 s41, s47, s53
	s_cselect_b32 s85, s46, s52
	s_add_u32 s50, s50, 0x80080
	s_addc_u32 s51, s51, 0
	s_add_u32 s86, s52, 0x100
	s_addc_u32 s87, s53, 0
	s_mov_b32 s88, -2
	s_add_u32 s28, s50, 0xfff80080
	s_addc_u32 s29, s51, -1
	s_add_i32 s89, 0, 0x10000
	s_cmp_eq_u32 s88, 28
	s_cselect_b32 s53, s43, s29
	s_cselect_b32 s52, s84, s28
	s_cselect_b32 s29, s41, s87
	s_cselect_b32 s28, s85, s86
	s_add_i32 s92, 0, 0x14000
	v_add_u32_e32 v158, s89, v147
	v_add_u32_e32 v174, s92, v147
	ds_read_b128 v[142:145], v158
	ds_read_b128 v[150:153], v158 offset:1024
	ds_read_b128 v[154:157], v158 offset:2048
	ds_read_b128 v[158:161], v158 offset:3072
	ds_read_b128 v[162:165], v174
	ds_read_b128 v[166:169], v174 offset:1024
	ds_read_b128 v[170:173], v174 offset:2048
	ds_read_b128 v[174:177], v174 offset:3072
	s_add_i32 m0, s36, 0xc000
	ds_read_b128 v[178:181], v149
	ds_read_b128 v[182:185], v149 offset:1024
	ds_read_b128 v[186:189], v149 offset:2048
	ds_read_b128 v[190:193], v149 offset:3072
	ds_read_b128 v[194:197], v149 offset:4096
	ds_read_b128 v[198:201], v149 offset:5120
	ds_read_b128 v[202:205], v149 offset:6144
	ds_read_b128 v[224:227], v149 offset:7168
	global_load_lds_dwordx4 v138, s[50:51]
	s_add_i32 m0, s36, 0xe000
	s_nop 0
	global_load_lds_dwordx4 v140, s[50:51]
	s_waitcnt vmcnt(8)
	s_waitcnt lgkmcnt(0)
	s_barrier
	s_setprio 1
	s_waitcnt lgkmcnt(0)
	v_mfma_f32_16x16x32_bf16 v[126:129], v[142:145], v[178:181], 0
	v_mfma_f32_16x16x32_bf16 v[122:125], v[154:157], v[178:181], 0
	v_mfma_f32_16x16x32_bf16 v[118:121], v[142:145], v[186:189], 0
	v_mfma_f32_16x16x32_bf16 v[110:113], v[154:157], v[186:189], 0
	v_mfma_f32_16x16x32_bf16 v[102:105], v[142:145], v[194:197], 0
	v_mfma_f32_16x16x32_bf16 v[94:97], v[154:157], v[194:197], 0
	v_mfma_f32_16x16x32_bf16 v[86:89], v[142:145], v[202:205], 0
	v_mfma_f32_16x16x32_bf16 v[78:81], v[154:157], v[202:205], 0
	v_mfma_f32_16x16x32_bf16 v[126:129], v[150:153], v[182:185], v[126:129]
	v_mfma_f32_16x16x32_bf16 v[122:125], v[158:161], v[182:185], v[122:125]
	v_mfma_f32_16x16x32_bf16 v[118:121], v[150:153], v[190:193], v[118:121]
	v_mfma_f32_16x16x32_bf16 v[110:113], v[158:161], v[190:193], v[110:113]
	v_mfma_f32_16x16x32_bf16 v[102:105], v[150:153], v[198:201], v[102:105]
	v_mfma_f32_16x16x32_bf16 v[94:97], v[158:161], v[198:201], v[94:97]
	v_mfma_f32_16x16x32_bf16 v[86:89], v[150:153], v[224:227], v[86:89]
	v_mfma_f32_16x16x32_bf16 v[78:81], v[158:161], v[224:227], v[78:81]
	s_setprio 0
	s_setprio 1
	v_mfma_f32_16x16x32_bf16 v[114:117], v[162:165], v[178:181], 0
	v_mfma_f32_16x16x32_bf16 v[106:109], v[170:173], v[178:181], 0
	v_mfma_f32_16x16x32_bf16 v[98:101], v[162:165], v[186:189], 0
	v_mfma_f32_16x16x32_bf16 v[90:93], v[170:173], v[186:189], 0
	v_mfma_f32_16x16x32_bf16 v[82:85], v[162:165], v[194:197], 0
	v_mfma_f32_16x16x32_bf16 v[74:77], v[170:173], v[194:197], 0
	v_mfma_f32_16x16x32_bf16 v[70:73], v[162:165], v[202:205], 0
	v_mfma_f32_16x16x32_bf16 v[66:69], v[170:173], v[202:205], 0
	v_mfma_f32_16x16x32_bf16 v[114:117], v[166:169], v[182:185], v[114:117]
	v_mfma_f32_16x16x32_bf16 v[106:109], v[174:177], v[182:185], v[106:109]
	v_mfma_f32_16x16x32_bf16 v[98:101], v[166:169], v[190:193], v[98:101]
	v_mfma_f32_16x16x32_bf16 v[90:93], v[174:177], v[190:193], v[90:93]
	v_mfma_f32_16x16x32_bf16 v[82:85], v[166:169], v[198:201], v[82:85]
	v_mfma_f32_16x16x32_bf16 v[74:77], v[174:177], v[198:201], v[74:77]
	v_mfma_f32_16x16x32_bf16 v[70:73], v[166:169], v[224:227], v[70:73]
	v_mfma_f32_16x16x32_bf16 v[66:69], v[174:177], v[224:227], v[66:69]
	s_setprio 0
	s_barrier
	s_add_i32 s89, s89, s26
	s_mov_b32 m0, s89
	ds_read_b128 v[178:181], v149 offset:16384
	ds_read_b128 v[182:185], v149 offset:17408
	ds_read_b128 v[186:189], v149 offset:18432
	ds_read_b128 v[190:193], v149 offset:19456
	ds_read_b128 v[194:197], v149 offset:20480
	ds_read_b128 v[198:201], v149 offset:21504
	ds_read_b128 v[202:205], v149 offset:22528
	ds_read_b128 v[224:227], v149 offset:23552
	global_load_lds_dwordx4 v134, s[28:29]
	s_add_i32 m0, s89, 0x2000
	s_add_u32 s90, s28, 0x80000
	s_addc_u32 s91, s29, 0
	s_add_i32 s89, s92, s26
	global_load_lds_dwordx4 v130, s[28:29]
	s_mov_b32 m0, s89
	v_lshl_add_u64 v[232:233], s[52:53], 0, v[132:133]
	global_load_lds_dwordx4 v134, s[90:91]
	s_add_i32 m0, s89, 0x2000
	s_nop 0
	global_load_lds_dwordx4 v130, s[90:91]
	v_lshl_add_u64 v[230:231], s[52:53], 0, v[136:137]
	s_mov_b32 m0, s36
	s_nop 0
	global_load_lds_dwordx4 v[230:231], off
	s_mov_b32 m0, s37
	s_nop 0
	global_load_lds_dwordx4 v[232:233], off
	s_waitcnt vmcnt(8)
	s_waitcnt lgkmcnt(0)
	s_barrier
	s_setprio 1
	s_waitcnt lgkmcnt(0)
	v_mfma_f32_16x16x32_bf16 v[62:65], v[142:145], v[178:181], 0
	v_mfma_f32_16x16x32_bf16 v[58:61], v[154:157], v[178:181], 0
	v_mfma_f32_16x16x32_bf16 v[54:57], v[142:145], v[186:189], 0
	v_mfma_f32_16x16x32_bf16 v[46:49], v[154:157], v[186:189], 0
	v_mfma_f32_16x16x32_bf16 v[38:41], v[142:145], v[194:197], 0
	v_mfma_f32_16x16x32_bf16 v[30:33], v[154:157], v[194:197], 0
	v_mfma_f32_16x16x32_bf16 v[22:25], v[142:145], v[202:205], 0
	v_mfma_f32_16x16x32_bf16 v[12:15], v[154:157], v[202:205], 0
	v_mfma_f32_16x16x32_bf16 v[62:65], v[150:153], v[182:185], v[62:65]
	v_mfma_f32_16x16x32_bf16 v[58:61], v[158:161], v[182:185], v[58:61]
	v_mfma_f32_16x16x32_bf16 v[54:57], v[150:153], v[190:193], v[54:57]
	v_mfma_f32_16x16x32_bf16 v[46:49], v[158:161], v[190:193], v[46:49]
	v_mfma_f32_16x16x32_bf16 v[38:41], v[150:153], v[198:201], v[38:41]
	v_mfma_f32_16x16x32_bf16 v[30:33], v[158:161], v[198:201], v[30:33]
	v_mfma_f32_16x16x32_bf16 v[22:25], v[150:153], v[224:227], v[22:25]
	v_mfma_f32_16x16x32_bf16 v[12:15], v[158:161], v[224:227], v[12:15]
	s_setprio 0
	s_setprio 1
	v_mfma_f32_16x16x32_bf16 v[50:53], v[162:165], v[178:181], 0
	v_mfma_f32_16x16x32_bf16 v[42:45], v[170:173], v[178:181], 0
	v_mfma_f32_16x16x32_bf16 v[34:37], v[162:165], v[186:189], 0
	v_mfma_f32_16x16x32_bf16 v[26:29], v[170:173], v[186:189], 0
	v_mfma_f32_16x16x32_bf16 v[18:21], v[162:165], v[194:197], 0
	v_mfma_f32_16x16x32_bf16 v[8:11], v[170:173], v[194:197], 0
	v_mfma_f32_16x16x32_bf16 v[4:7], v[162:165], v[202:205], 0
	v_mfma_f32_16x16x32_bf16 v[0:3], v[170:173], v[202:205], 0
	v_mfma_f32_16x16x32_bf16 v[50:53], v[166:169], v[182:185], v[50:53]
	v_mfma_f32_16x16x32_bf16 v[42:45], v[174:177], v[182:185], v[42:45]
	v_mfma_f32_16x16x32_bf16 v[34:37], v[166:169], v[190:193], v[34:37]
	v_mfma_f32_16x16x32_bf16 v[26:29], v[174:177], v[190:193], v[26:29]
	v_mfma_f32_16x16x32_bf16 v[18:21], v[166:169], v[198:201], v[18:21]
	v_mfma_f32_16x16x32_bf16 v[8:11], v[174:177], v[198:201], v[8:11]
	v_mfma_f32_16x16x32_bf16 v[4:7], v[166:169], v[224:227], v[4:7]
	v_mfma_f32_16x16x32_bf16 v[0:3], v[174:177], v[224:227], v[0:3]
	s_setprio 0
	s_barrier
	s_add_i32 s89, 0, 0x18000
	s_add_i32 s90, 0, 0x1c000
	v_add_u32_e32 v158, s89, v147
	v_add_u32_e32 v174, s90, v147
	ds_read_b128 v[142:145], v158
	ds_read_b128 v[150:153], v158 offset:1024
	ds_read_b128 v[154:157], v158 offset:2048
	ds_read_b128 v[158:161], v158 offset:3072
	ds_read_b128 v[162:165], v174
	ds_read_b128 v[166:169], v174 offset:1024
	ds_read_b128 v[170:173], v174 offset:2048
	ds_read_b128 v[174:177], v174 offset:3072
	s_add_u32 s52, s52, 0x80000
	s_addc_u32 s53, s53, 0
	s_mov_b32 m0, s49
	ds_read_b128 v[178:181], v149 offset:32768
	ds_read_b128 v[182:185], v149 offset:33792
	ds_read_b128 v[186:189], v149 offset:34816
	ds_read_b128 v[190:193], v149 offset:35840
	ds_read_b128 v[194:197], v149 offset:36864
	ds_read_b128 v[198:201], v149 offset:37888
	ds_read_b128 v[202:205], v149 offset:38912
	ds_read_b128 v[224:227], v149 offset:39936
	global_load_lds_dwordx4 v136, s[52:53]
	s_mov_b32 m0, s56
	s_nop 0
	global_load_lds_dwordx4 v132, s[52:53]
	s_waitcnt vmcnt(8)
	s_waitcnt lgkmcnt(0)
	s_barrier
	s_setprio 1
	s_waitcnt lgkmcnt(0)
	v_mfma_f32_16x16x32_bf16 v[126:129], v[142:145], v[178:181], v[126:129]
	v_mfma_f32_16x16x32_bf16 v[122:125], v[154:157], v[178:181], v[122:125]
	v_mfma_f32_16x16x32_bf16 v[118:121], v[142:145], v[186:189], v[118:121]
	v_mfma_f32_16x16x32_bf16 v[110:113], v[154:157], v[186:189], v[110:113]
	v_mfma_f32_16x16x32_bf16 v[102:105], v[142:145], v[194:197], v[102:105]
	v_mfma_f32_16x16x32_bf16 v[94:97], v[154:157], v[194:197], v[94:97]
	v_mfma_f32_16x16x32_bf16 v[86:89], v[142:145], v[202:205], v[86:89]
	v_mfma_f32_16x16x32_bf16 v[78:81], v[154:157], v[202:205], v[78:81]
	v_mfma_f32_16x16x32_bf16 v[126:129], v[150:153], v[182:185], v[126:129]
	v_mfma_f32_16x16x32_bf16 v[122:125], v[158:161], v[182:185], v[122:125]
	v_mfma_f32_16x16x32_bf16 v[118:121], v[150:153], v[190:193], v[118:121]
	v_mfma_f32_16x16x32_bf16 v[110:113], v[158:161], v[190:193], v[110:113]
	v_mfma_f32_16x16x32_bf16 v[102:105], v[150:153], v[198:201], v[102:105]
	v_mfma_f32_16x16x32_bf16 v[94:97], v[158:161], v[198:201], v[94:97]
	v_mfma_f32_16x16x32_bf16 v[86:89], v[150:153], v[224:227], v[86:89]
	v_mfma_f32_16x16x32_bf16 v[78:81], v[158:161], v[224:227], v[78:81]
	s_setprio 0
	s_setprio 1
	v_mfma_f32_16x16x32_bf16 v[114:117], v[162:165], v[178:181], v[114:117]
	v_mfma_f32_16x16x32_bf16 v[106:109], v[170:173], v[178:181], v[106:109]
	v_mfma_f32_16x16x32_bf16 v[98:101], v[162:165], v[186:189], v[98:101]
	v_mfma_f32_16x16x32_bf16 v[90:93], v[170:173], v[186:189], v[90:93]
	v_mfma_f32_16x16x32_bf16 v[82:85], v[162:165], v[194:197], v[82:85]
	v_mfma_f32_16x16x32_bf16 v[74:77], v[170:173], v[194:197], v[74:77]
	v_mfma_f32_16x16x32_bf16 v[70:73], v[162:165], v[202:205], v[70:73]
	v_mfma_f32_16x16x32_bf16 v[66:69], v[170:173], v[202:205], v[66:69]
	v_mfma_f32_16x16x32_bf16 v[114:117], v[166:169], v[182:185], v[114:117]
	v_mfma_f32_16x16x32_bf16 v[106:109], v[174:177], v[182:185], v[106:109]
	v_mfma_f32_16x16x32_bf16 v[98:101], v[166:169], v[190:193], v[98:101]
	v_mfma_f32_16x16x32_bf16 v[90:93], v[174:177], v[190:193], v[90:93]
	v_mfma_f32_16x16x32_bf16 v[82:85], v[166:169], v[198:201], v[82:85]
	v_mfma_f32_16x16x32_bf16 v[74:77], v[174:177], v[198:201], v[74:77]
	v_mfma_f32_16x16x32_bf16 v[70:73], v[166:169], v[224:227], v[70:73]
	v_mfma_f32_16x16x32_bf16 v[66:69], v[174:177], v[224:227], v[66:69]
	s_setprio 0
	s_barrier
	s_add_i32 s52, s89, s26
	s_add_u32 s28, s28, 0x80
	s_addc_u32 s29, s29, 0
	s_mov_b32 m0, s52
	ds_read_b128 v[178:181], v149 offset:49152
	ds_read_b128 v[182:185], v149 offset:50176
	ds_read_b128 v[186:189], v149 offset:51200
	ds_read_b128 v[190:193], v149 offset:52224
	ds_read_b128 v[194:197], v149 offset:53248
	ds_read_b128 v[198:201], v149 offset:54272
	ds_read_b128 v[202:205], v149 offset:55296
	ds_read_b128 v[224:227], v149 offset:56320
	global_load_lds_dwordx4 v134, s[28:29]
	s_add_i32 m0, s52, 0x2000
	s_add_i32 s52, s90, s26
	global_load_lds_dwordx4 v130, s[28:29]
	s_add_u32 s28, s28, 0x80000
	s_addc_u32 s29, s29, 0
	s_mov_b32 m0, s52
	s_nop 0
	global_load_lds_dwordx4 v134, s[28:29]
	s_add_i32 m0, s52, 0x2000
	s_nop 0
	global_load_lds_dwordx4 v130, s[28:29]
	v_lshl_add_u64 v[206:207], v[230:231], 0, s[34:35]
	s_mov_b32 m0, s57
	s_nop 0
	global_load_lds_dwordx4 v[206:207], off
	v_lshl_add_u64 v[206:207], v[232:233], 0, s[34:35]
	s_mov_b32 m0, s58
	s_nop 0
	global_load_lds_dwordx4 v[206:207], off
	s_waitcnt vmcnt(8)
	s_waitcnt lgkmcnt(0)
	s_barrier
	s_setprio 1
	s_waitcnt lgkmcnt(0)
	v_mfma_f32_16x16x32_bf16 v[62:65], v[142:145], v[178:181], v[62:65]
	v_mfma_f32_16x16x32_bf16 v[58:61], v[154:157], v[178:181], v[58:61]
	v_mfma_f32_16x16x32_bf16 v[54:57], v[142:145], v[186:189], v[54:57]
	v_mfma_f32_16x16x32_bf16 v[46:49], v[154:157], v[186:189], v[46:49]
	v_mfma_f32_16x16x32_bf16 v[38:41], v[142:145], v[194:197], v[38:41]
	v_mfma_f32_16x16x32_bf16 v[30:33], v[154:157], v[194:197], v[30:33]
	v_mfma_f32_16x16x32_bf16 v[22:25], v[142:145], v[202:205], v[22:25]
	v_mfma_f32_16x16x32_bf16 v[12:15], v[154:157], v[202:205], v[12:15]
	v_mfma_f32_16x16x32_bf16 v[62:65], v[150:153], v[182:185], v[62:65]
	v_mfma_f32_16x16x32_bf16 v[58:61], v[158:161], v[182:185], v[58:61]
	v_mfma_f32_16x16x32_bf16 v[54:57], v[150:153], v[190:193], v[54:57]
	v_mfma_f32_16x16x32_bf16 v[46:49], v[158:161], v[190:193], v[46:49]
	v_mfma_f32_16x16x32_bf16 v[38:41], v[150:153], v[198:201], v[38:41]
	v_mfma_f32_16x16x32_bf16 v[30:33], v[158:161], v[198:201], v[30:33]
	v_mfma_f32_16x16x32_bf16 v[22:25], v[150:153], v[224:227], v[22:25]
	v_mfma_f32_16x16x32_bf16 v[12:15], v[158:161], v[224:227], v[12:15]
	s_setprio 0
	s_setprio 1
	v_mfma_f32_16x16x32_bf16 v[50:53], v[162:165], v[178:181], v[50:53]
	v_mfma_f32_16x16x32_bf16 v[42:45], v[170:173], v[178:181], v[42:45]
	v_mfma_f32_16x16x32_bf16 v[34:37], v[162:165], v[186:189], v[34:37]
	v_mfma_f32_16x16x32_bf16 v[26:29], v[170:173], v[186:189], v[26:29]
	v_mfma_f32_16x16x32_bf16 v[18:21], v[162:165], v[194:197], v[18:21]
	v_mfma_f32_16x16x32_bf16 v[8:11], v[170:173], v[194:197], v[8:11]
	v_mfma_f32_16x16x32_bf16 v[4:7], v[162:165], v[202:205], v[4:7]
	v_mfma_f32_16x16x32_bf16 v[0:3], v[170:173], v[202:205], v[0:3]
	v_mfma_f32_16x16x32_bf16 v[50:53], v[166:169], v[182:185], v[50:53]
	v_mfma_f32_16x16x32_bf16 v[42:45], v[174:177], v[182:185], v[42:45]
	v_mfma_f32_16x16x32_bf16 v[34:37], v[166:169], v[190:193], v[34:37]
	v_mfma_f32_16x16x32_bf16 v[26:29], v[174:177], v[190:193], v[26:29]
	v_mfma_f32_16x16x32_bf16 v[18:21], v[166:169], v[198:201], v[18:21]
	v_mfma_f32_16x16x32_bf16 v[8:11], v[174:177], v[198:201], v[8:11]
	v_mfma_f32_16x16x32_bf16 v[4:7], v[166:169], v[224:227], v[4:7]
	v_mfma_f32_16x16x32_bf16 v[0:3], v[174:177], v[224:227], v[0:3]
	s_setprio 0
	s_barrier
	s_add_i32 s88, s88, 2
	s_add_u32 s50, s50, 0x100
	s_addc_u32 s51, s51, 0
	s_add_u32 s86, s86, 0x100
	s_addc_u32 s87, s87, 0
	s_cmp_gt_u32 s88, 29
	s_cbranch_scc1 .Lpz_B_exit

.LBB0_648:
	s_ashr_i32 s19, s18, 31
	s_lshl_b64 s[28:29], s[18:19], 18
	v_readlane_b32 s19, v255, 10
	s_add_u32 s42, s19, s28
	v_readlane_b32 s19, v255, 11
	s_addc_u32 s43, s19, s29
	s_and_b64 s[28:29], s[40:41], exec
	s_cselect_b32 s19, s43, s47
	s_cselect_b32 s23, s42, s46
	s_add_u32 s40, s48, 0x80080
	s_addc_u32 s41, s49, 0
	s_add_u32 s48, s46, 0x100
	s_addc_u32 s49, s47, 0
	s_mov_b32 s87, -2
	s_add_u32 s28, s40, 0xfff80080
	s_addc_u32 s29, s41, -1
	s_add_i32 s88, 0, 0x10000
	s_cmp_eq_u32 s87, 4
	s_cselect_b32 s47, s27, s29
	s_cselect_b32 s46, s26, s28
	v_add_u32_e32 v140, s88, v143
	s_cselect_b32 s29, s19, s49
	s_cselect_b32 s28, s23, s48
	s_add_i32 s90, 0, 0x14000
	ds_read_b128 v[146:149], v140
	ds_read_b128 v[150:153], v140 offset:1024
	ds_read_b128 v[154:157], v140 offset:2048
	ds_read_b128 v[158:161], v140 offset:3072
	v_add_u32_e32 v140, s90, v143
	ds_read_b128 v[162:165], v140
	ds_read_b128 v[166:169], v140 offset:1024
	ds_read_b128 v[170:173], v140 offset:2048
	ds_read_b128 v[174:177], v140 offset:3072
	s_add_i32 m0, s45, 0xc000
	ds_read_b128 v[178:181], v145
	ds_read_b128 v[182:185], v145 offset:1024
	ds_read_b128 v[186:189], v145 offset:2048
	ds_read_b128 v[190:193], v145 offset:3072
	ds_read_b128 v[194:197], v145 offset:4096
	ds_read_b128 v[198:201], v145 offset:5120
	ds_read_b128 v[202:205], v145 offset:6144
	ds_read_b128 v[224:227], v145 offset:7168
	global_load_lds_dwordx4 v136, s[40:41]
	s_add_i32 m0, s45, 0xe000
	s_nop 0
	global_load_lds_dwordx4 v138, s[40:41]
	s_waitcnt vmcnt(8)
	s_waitcnt lgkmcnt(0)
	s_barrier
	s_setprio 1
	s_waitcnt lgkmcnt(0)
	v_mfma_f32_16x16x32_bf16 v[126:129], v[146:149], v[178:181], 0
	v_mfma_f32_16x16x32_bf16 v[122:125], v[154:157], v[178:181], 0
	v_mfma_f32_16x16x32_bf16 v[118:121], v[146:149], v[186:189], 0
	v_mfma_f32_16x16x32_bf16 v[110:113], v[154:157], v[186:189], 0
	v_mfma_f32_16x16x32_bf16 v[102:105], v[146:149], v[194:197], 0
	v_mfma_f32_16x16x32_bf16 v[94:97], v[154:157], v[194:197], 0
	v_mfma_f32_16x16x32_bf16 v[86:89], v[146:149], v[202:205], 0
	v_mfma_f32_16x16x32_bf16 v[78:81], v[154:157], v[202:205], 0
	v_mfma_f32_16x16x32_bf16 v[126:129], v[150:153], v[182:185], v[126:129]
	v_mfma_f32_16x16x32_bf16 v[122:125], v[158:161], v[182:185], v[122:125]
	v_mfma_f32_16x16x32_bf16 v[118:121], v[150:153], v[190:193], v[118:121]
	v_mfma_f32_16x16x32_bf16 v[110:113], v[158:161], v[190:193], v[110:113]
	v_mfma_f32_16x16x32_bf16 v[102:105], v[150:153], v[198:201], v[102:105]
	v_mfma_f32_16x16x32_bf16 v[94:97], v[158:161], v[198:201], v[94:97]
	v_mfma_f32_16x16x32_bf16 v[86:89], v[150:153], v[224:227], v[86:89]
	v_mfma_f32_16x16x32_bf16 v[78:81], v[158:161], v[224:227], v[78:81]
	s_setprio 0
	s_setprio 1
	v_mfma_f32_16x16x32_bf16 v[114:117], v[162:165], v[178:181], 0
	v_mfma_f32_16x16x32_bf16 v[106:109], v[170:173], v[178:181], 0
	v_mfma_f32_16x16x32_bf16 v[98:101], v[162:165], v[186:189], 0
	v_mfma_f32_16x16x32_bf16 v[90:93], v[170:173], v[186:189], 0
	v_mfma_f32_16x16x32_bf16 v[82:85], v[162:165], v[194:197], 0
	v_mfma_f32_16x16x32_bf16 v[74:77], v[170:173], v[194:197], 0
	v_mfma_f32_16x16x32_bf16 v[70:73], v[162:165], v[202:205], 0
	v_mfma_f32_16x16x32_bf16 v[66:69], v[170:173], v[202:205], 0
	v_mfma_f32_16x16x32_bf16 v[114:117], v[166:169], v[182:185], v[114:117]
	v_mfma_f32_16x16x32_bf16 v[106:109], v[174:177], v[182:185], v[106:109]
	v_mfma_f32_16x16x32_bf16 v[98:101], v[166:169], v[190:193], v[98:101]
	v_mfma_f32_16x16x32_bf16 v[90:93], v[174:177], v[190:193], v[90:93]
	v_mfma_f32_16x16x32_bf16 v[82:85], v[166:169], v[198:201], v[82:85]
	v_mfma_f32_16x16x32_bf16 v[74:77], v[174:177], v[198:201], v[74:77]
	v_mfma_f32_16x16x32_bf16 v[70:73], v[166:169], v[224:227], v[70:73]
	v_mfma_f32_16x16x32_bf16 v[66:69], v[174:177], v[224:227], v[66:69]
	s_setprio 0
	s_barrier
	s_add_i32 s88, s88, s37
	s_mov_b32 m0, s88
	ds_read_b128 v[178:181], v145 offset:16384
	ds_read_b128 v[182:185], v145 offset:17408
	ds_read_b128 v[186:189], v145 offset:18432
	ds_read_b128 v[190:193], v145 offset:19456
	ds_read_b128 v[194:197], v145 offset:20480
	ds_read_b128 v[198:201], v145 offset:21504
	ds_read_b128 v[202:205], v145 offset:22528
	ds_read_b128 v[224:227], v145 offset:23552
	global_load_lds_dwordx4 v16, s[28:29]
	s_add_i32 m0, s88, 0x2000
	s_add_u32 s88, s28, 0x20000
	s_addc_u32 s89, s29, 0
	s_add_i32 s90, s90, s37
	global_load_lds_dwordx4 v130, s[28:29]
	s_mov_b32 m0, s90
	v_lshl_add_u64 v[230:231], s[46:47], 0, v[132:133]
	global_load_lds_dwordx4 v16, s[88:89]
	s_add_i32 m0, s90, 0x2000
	s_nop 0
	global_load_lds_dwordx4 v130, s[88:89]
	v_lshl_add_u64 v[228:229], s[46:47], 0, v[134:135]
	s_mov_b32 m0, s45
	s_nop 0
	global_load_lds_dwordx4 v[228:229], off
	s_mov_b32 m0, s53
	s_nop 0
	global_load_lds_dwordx4 v[230:231], off
	s_waitcnt vmcnt(8)
	s_waitcnt lgkmcnt(0)
	s_barrier
	s_setprio 1
	s_waitcnt lgkmcnt(0)
	v_mfma_f32_16x16x32_bf16 v[62:65], v[146:149], v[178:181], 0
	v_mfma_f32_16x16x32_bf16 v[58:61], v[154:157], v[178:181], 0
	v_mfma_f32_16x16x32_bf16 v[54:57], v[146:149], v[186:189], 0
	v_mfma_f32_16x16x32_bf16 v[46:49], v[154:157], v[186:189], 0
	v_mfma_f32_16x16x32_bf16 v[38:41], v[146:149], v[194:197], 0
	v_mfma_f32_16x16x32_bf16 v[30:33], v[154:157], v[194:197], 0
	v_mfma_f32_16x16x32_bf16 v[22:25], v[146:149], v[202:205], 0
	v_mfma_f32_16x16x32_bf16 v[12:15], v[154:157], v[202:205], 0
	v_mfma_f32_16x16x32_bf16 v[62:65], v[150:153], v[182:185], v[62:65]
	v_mfma_f32_16x16x32_bf16 v[58:61], v[158:161], v[182:185], v[58:61]
	v_mfma_f32_16x16x32_bf16 v[54:57], v[150:153], v[190:193], v[54:57]
	v_mfma_f32_16x16x32_bf16 v[46:49], v[158:161], v[190:193], v[46:49]
	v_mfma_f32_16x16x32_bf16 v[38:41], v[150:153], v[198:201], v[38:41]
	v_mfma_f32_16x16x32_bf16 v[30:33], v[158:161], v[198:201], v[30:33]
	v_mfma_f32_16x16x32_bf16 v[22:25], v[150:153], v[224:227], v[22:25]
	v_mfma_f32_16x16x32_bf16 v[12:15], v[158:161], v[224:227], v[12:15]
	s_setprio 0
	s_setprio 1
	v_mfma_f32_16x16x32_bf16 v[50:53], v[162:165], v[178:181], 0
	v_mfma_f32_16x16x32_bf16 v[42:45], v[170:173], v[178:181], 0
	v_mfma_f32_16x16x32_bf16 v[34:37], v[162:165], v[186:189], 0
	v_mfma_f32_16x16x32_bf16 v[26:29], v[170:173], v[186:189], 0
	v_mfma_f32_16x16x32_bf16 v[18:21], v[162:165], v[194:197], 0
	v_mfma_f32_16x16x32_bf16 v[8:11], v[170:173], v[194:197], 0
	v_mfma_f32_16x16x32_bf16 v[4:7], v[162:165], v[202:205], 0
	v_mfma_f32_16x16x32_bf16 v[0:3], v[170:173], v[202:205], 0
	v_mfma_f32_16x16x32_bf16 v[50:53], v[166:169], v[182:185], v[50:53]
	v_mfma_f32_16x16x32_bf16 v[42:45], v[174:177], v[182:185], v[42:45]
	v_mfma_f32_16x16x32_bf16 v[34:37], v[166:169], v[190:193], v[34:37]
	v_mfma_f32_16x16x32_bf16 v[26:29], v[174:177], v[190:193], v[26:29]
	v_mfma_f32_16x16x32_bf16 v[18:21], v[166:169], v[198:201], v[18:21]
	v_mfma_f32_16x16x32_bf16 v[8:11], v[174:177], v[198:201], v[8:11]
	v_mfma_f32_16x16x32_bf16 v[4:7], v[166:169], v[224:227], v[4:7]
	v_mfma_f32_16x16x32_bf16 v[0:3], v[174:177], v[224:227], v[0:3]
	s_setprio 0
	s_barrier
	s_add_i32 s88, 0, 0x18000
	s_add_i32 s89, 0, 0x1c000
	v_add_u32_e32 v158, s88, v143
	v_add_u32_e32 v174, s89, v143
	ds_read_b128 v[146:149], v158
	ds_read_b128 v[150:153], v158 offset:1024
	ds_read_b128 v[154:157], v158 offset:2048
	ds_read_b128 v[158:161], v158 offset:3072
	ds_read_b128 v[162:165], v174
	ds_read_b128 v[166:169], v174 offset:1024
	ds_read_b128 v[170:173], v174 offset:2048
	ds_read_b128 v[174:177], v174 offset:3072
	s_add_u32 s46, s46, 0x80000
	s_addc_u32 s47, s47, 0
	s_mov_b32 m0, s58
	ds_read_b128 v[178:181], v145 offset:32768
	ds_read_b128 v[182:185], v145 offset:33792
	ds_read_b128 v[186:189], v145 offset:34816
	ds_read_b128 v[190:193], v145 offset:35840
	ds_read_b128 v[194:197], v145 offset:36864
	ds_read_b128 v[198:201], v145 offset:37888
	ds_read_b128 v[202:205], v145 offset:38912
	ds_read_b128 v[224:227], v145 offset:39936
	global_load_lds_dwordx4 v134, s[46:47]
	s_mov_b32 m0, s59
	s_nop 0
	global_load_lds_dwordx4 v132, s[46:47]
	s_waitcnt vmcnt(8)
	s_waitcnt lgkmcnt(0)
	s_barrier
	s_setprio 1
	s_waitcnt lgkmcnt(0)
	v_mfma_f32_16x16x32_bf16 v[126:129], v[146:149], v[178:181], v[126:129]
	v_mfma_f32_16x16x32_bf16 v[122:125], v[154:157], v[178:181], v[122:125]
	v_mfma_f32_16x16x32_bf16 v[118:121], v[146:149], v[186:189], v[118:121]
	v_mfma_f32_16x16x32_bf16 v[110:113], v[154:157], v[186:189], v[110:113]
	v_mfma_f32_16x16x32_bf16 v[102:105], v[146:149], v[194:197], v[102:105]
	v_mfma_f32_16x16x32_bf16 v[94:97], v[154:157], v[194:197], v[94:97]
	v_mfma_f32_16x16x32_bf16 v[86:89], v[146:149], v[202:205], v[86:89]
	v_mfma_f32_16x16x32_bf16 v[78:81], v[154:157], v[202:205], v[78:81]
	v_mfma_f32_16x16x32_bf16 v[126:129], v[150:153], v[182:185], v[126:129]
	v_mfma_f32_16x16x32_bf16 v[122:125], v[158:161], v[182:185], v[122:125]
	v_mfma_f32_16x16x32_bf16 v[118:121], v[150:153], v[190:193], v[118:121]
	v_mfma_f32_16x16x32_bf16 v[110:113], v[158:161], v[190:193], v[110:113]
	v_mfma_f32_16x16x32_bf16 v[102:105], v[150:153], v[198:201], v[102:105]
	v_mfma_f32_16x16x32_bf16 v[94:97], v[158:161], v[198:201], v[94:97]
	v_mfma_f32_16x16x32_bf16 v[86:89], v[150:153], v[224:227], v[86:89]
	v_mfma_f32_16x16x32_bf16 v[78:81], v[158:161], v[224:227], v[78:81]
	s_setprio 0
	s_setprio 1
	v_mfma_f32_16x16x32_bf16 v[114:117], v[162:165], v[178:181], v[114:117]
	v_mfma_f32_16x16x32_bf16 v[106:109], v[170:173], v[178:181], v[106:109]
	v_mfma_f32_16x16x32_bf16 v[98:101], v[162:165], v[186:189], v[98:101]
	v_mfma_f32_16x16x32_bf16 v[90:93], v[170:173], v[186:189], v[90:93]
	v_mfma_f32_16x16x32_bf16 v[82:85], v[162:165], v[194:197], v[82:85]
	v_mfma_f32_16x16x32_bf16 v[74:77], v[170:173], v[194:197], v[74:77]
	v_mfma_f32_16x16x32_bf16 v[70:73], v[162:165], v[202:205], v[70:73]
	v_mfma_f32_16x16x32_bf16 v[66:69], v[170:173], v[202:205], v[66:69]
	v_mfma_f32_16x16x32_bf16 v[114:117], v[166:169], v[182:185], v[114:117]
	v_mfma_f32_16x16x32_bf16 v[106:109], v[174:177], v[182:185], v[106:109]
	v_mfma_f32_16x16x32_bf16 v[98:101], v[166:169], v[190:193], v[98:101]
	v_mfma_f32_16x16x32_bf16 v[90:93], v[174:177], v[190:193], v[90:93]
	v_mfma_f32_16x16x32_bf16 v[82:85], v[166:169], v[198:201], v[82:85]
	v_mfma_f32_16x16x32_bf16 v[74:77], v[174:177], v[198:201], v[74:77]
	v_mfma_f32_16x16x32_bf16 v[70:73], v[166:169], v[224:227], v[70:73]
	v_mfma_f32_16x16x32_bf16 v[66:69], v[174:177], v[224:227], v[66:69]
	s_setprio 0
	s_barrier
	s_add_i32 s46, s88, s37
	s_add_u32 s28, s28, 0x80
	s_addc_u32 s29, s29, 0
	s_mov_b32 m0, s46
	ds_read_b128 v[178:181], v145 offset:49152
	ds_read_b128 v[182:185], v145 offset:50176
	ds_read_b128 v[186:189], v145 offset:51200
	ds_read_b128 v[190:193], v145 offset:52224
	ds_read_b128 v[194:197], v145 offset:53248
	ds_read_b128 v[198:201], v145 offset:54272
	ds_read_b128 v[202:205], v145 offset:55296
	ds_read_b128 v[224:227], v145 offset:56320
	global_load_lds_dwordx4 v16, s[28:29]
	s_add_i32 m0, s46, 0x2000
	s_add_i32 s46, s89, s37
	global_load_lds_dwordx4 v130, s[28:29]
	s_add_u32 s28, s28, 0x20000
	s_addc_u32 s29, s29, 0
	s_mov_b32 m0, s46
	s_nop 0
	global_load_lds_dwordx4 v16, s[28:29]
	s_add_i32 m0, s46, 0x2000
	s_nop 0
	global_load_lds_dwordx4 v130, s[28:29]
	v_lshl_add_u64 v[140:141], v[228:229], 0, s[34:35]
	s_mov_b32 m0, s83
	s_nop 0
	global_load_lds_dwordx4 v[140:141], off
	v_lshl_add_u64 v[140:141], v[230:231], 0, s[34:35]
	s_mov_b32 m0, s84
	s_nop 0
	global_load_lds_dwordx4 v[140:141], off
	s_waitcnt vmcnt(8)
	s_waitcnt lgkmcnt(0)
	s_barrier
	s_setprio 1
	s_waitcnt lgkmcnt(0)
	v_mfma_f32_16x16x32_bf16 v[62:65], v[146:149], v[178:181], v[62:65]
	v_mfma_f32_16x16x32_bf16 v[58:61], v[154:157], v[178:181], v[58:61]
	v_mfma_f32_16x16x32_bf16 v[54:57], v[146:149], v[186:189], v[54:57]
	v_mfma_f32_16x16x32_bf16 v[46:49], v[154:157], v[186:189], v[46:49]
	v_mfma_f32_16x16x32_bf16 v[38:41], v[146:149], v[194:197], v[38:41]
	v_mfma_f32_16x16x32_bf16 v[30:33], v[154:157], v[194:197], v[30:33]
	v_mfma_f32_16x16x32_bf16 v[22:25], v[146:149], v[202:205], v[22:25]
	v_mfma_f32_16x16x32_bf16 v[12:15], v[154:157], v[202:205], v[12:15]
	v_mfma_f32_16x16x32_bf16 v[62:65], v[150:153], v[182:185], v[62:65]
	v_mfma_f32_16x16x32_bf16 v[58:61], v[158:161], v[182:185], v[58:61]
	v_mfma_f32_16x16x32_bf16 v[54:57], v[150:153], v[190:193], v[54:57]
	v_mfma_f32_16x16x32_bf16 v[46:49], v[158:161], v[190:193], v[46:49]
	v_mfma_f32_16x16x32_bf16 v[38:41], v[150:153], v[198:201], v[38:41]
	v_mfma_f32_16x16x32_bf16 v[30:33], v[158:161], v[198:201], v[30:33]
	v_mfma_f32_16x16x32_bf16 v[22:25], v[150:153], v[224:227], v[22:25]
	v_mfma_f32_16x16x32_bf16 v[12:15], v[158:161], v[224:227], v[12:15]
	s_setprio 0
	s_setprio 1
	v_mfma_f32_16x16x32_bf16 v[50:53], v[162:165], v[178:181], v[50:53]
	v_mfma_f32_16x16x32_bf16 v[42:45], v[170:173], v[178:181], v[42:45]
	v_mfma_f32_16x16x32_bf16 v[34:37], v[162:165], v[186:189], v[34:37]
	v_mfma_f32_16x16x32_bf16 v[26:29], v[170:173], v[186:189], v[26:29]
	v_mfma_f32_16x16x32_bf16 v[18:21], v[162:165], v[194:197], v[18:21]
	v_mfma_f32_16x16x32_bf16 v[8:11], v[170:173], v[194:197], v[8:11]
	v_mfma_f32_16x16x32_bf16 v[4:7], v[162:165], v[202:205], v[4:7]
	v_mfma_f32_16x16x32_bf16 v[0:3], v[170:173], v[202:205], v[0:3]
	v_mfma_f32_16x16x32_bf16 v[50:53], v[166:169], v[182:185], v[50:53]
	v_mfma_f32_16x16x32_bf16 v[42:45], v[174:177], v[182:185], v[42:45]
	v_mfma_f32_16x16x32_bf16 v[34:37], v[166:169], v[190:193], v[34:37]
	v_mfma_f32_16x16x32_bf16 v[26:29], v[174:177], v[190:193], v[26:29]
	v_mfma_f32_16x16x32_bf16 v[18:21], v[166:169], v[198:201], v[18:21]
	v_mfma_f32_16x16x32_bf16 v[8:11], v[174:177], v[198:201], v[8:11]
	v_mfma_f32_16x16x32_bf16 v[4:7], v[166:169], v[224:227], v[4:7]
	v_mfma_f32_16x16x32_bf16 v[0:3], v[174:177], v[224:227], v[0:3]
	s_setprio 0
	s_barrier
	s_add_i32 s87, s87, 2
	s_add_u32 s40, s40, 0x100
	s_addc_u32 s41, s41, 0
	s_add_u32 s48, s48, 0x100
	s_addc_u32 s49, s49, 0
	s_cmp_gt_u32 s87, 5
	s_cbranch_scc1 .Lpz_E_exit

.LBB0_716:
	s_ashr_i32 s23, s22, 31
	s_lshl_b64 s[26:27], s[22:23], 20
	s_add_u32 s26, s68, s26
	s_addc_u32 s27, s69, s27
	s_and_b64 s[28:29], s[38:39], exec
	s_cselect_b32 s23, s27, s45
	s_cselect_b32 s84, s26, s44
	s_ashr_i32 s19, s18, 31
	s_lshl_b64 s[28:29], s[18:19], 20
	v_readlane_b32 s19, v255, 12
	s_add_u32 s40, s19, s28
	v_readlane_b32 s19, v255, 13
	s_addc_u32 s41, s19, s29
	s_and_b64 s[28:29], s[38:39], exec
	s_cselect_b32 s19, s41, s47
	s_cselect_b32 s85, s40, s46
	s_add_u32 s44, s44, 0x80080
	s_addc_u32 s45, s45, 0
	s_add_u32 s86, s46, 0x100
	s_addc_u32 s87, s47, 0
	s_mov_b32 s88, -2
	s_add_u32 s28, s44, 0xfff80080
	s_addc_u32 s29, s45, -1
	s_add_i32 s89, 0, 0x10000
	s_cmp_eq_u32 s88, 28
	s_cselect_b32 s47, s23, s29
	s_cselect_b32 s46, s84, s28
	s_cselect_b32 s29, s19, s87
	s_cselect_b32 s28, s85, s86
	s_add_i32 s92, 0, 0x14000
	v_add_u32_e32 v148, s89, v224
	v_add_u32_e32 v164, s92, v224
	ds_read_b128 v[136:139], v148
	ds_read_b128 v[140:143], v148 offset:1024
	ds_read_b128 v[144:147], v148 offset:2048
	ds_read_b128 v[148:151], v148 offset:3072
	ds_read_b128 v[152:155], v164
	ds_read_b128 v[156:159], v164 offset:1024
	ds_read_b128 v[160:163], v164 offset:2048
	ds_read_b128 v[164:167], v164 offset:3072
	s_add_i32 m0, s43, 0xc000
	ds_read_b128 v[168:171], v226
	ds_read_b128 v[172:175], v226 offset:1024
	ds_read_b128 v[176:179], v226 offset:2048
	ds_read_b128 v[180:183], v226 offset:3072
	ds_read_b128 v[184:187], v226 offset:4096
	ds_read_b128 v[188:191], v226 offset:5120
	ds_read_b128 v[192:195], v226 offset:6144
	ds_read_b128 v[196:199], v226 offset:7168
	global_load_lds_dwordx4 v132, s[44:45]
	s_add_i32 m0, s43, 0xe000
	s_nop 0
	global_load_lds_dwordx4 v134, s[44:45]
	s_waitcnt vmcnt(8)
	s_waitcnt lgkmcnt(0)
	s_barrier
	s_setprio 1
	s_waitcnt lgkmcnt(0)
	v_mfma_f32_16x16x32_bf16 v[126:129], v[136:139], v[168:171], 0
	v_mfma_f32_16x16x32_bf16 v[122:125], v[144:147], v[168:171], 0
	v_mfma_f32_16x16x32_bf16 v[118:121], v[136:139], v[176:179], 0
	v_mfma_f32_16x16x32_bf16 v[114:117], v[144:147], v[176:179], 0
	v_mfma_f32_16x16x32_bf16 v[110:113], v[136:139], v[184:187], 0
	v_mfma_f32_16x16x32_bf16 v[106:109], v[144:147], v[184:187], 0
	v_mfma_f32_16x16x32_bf16 v[102:105], v[136:139], v[192:195], 0
	v_mfma_f32_16x16x32_bf16 v[98:101], v[144:147], v[192:195], 0
	v_mfma_f32_16x16x32_bf16 v[126:129], v[140:143], v[172:175], v[126:129]
	v_mfma_f32_16x16x32_bf16 v[122:125], v[148:151], v[172:175], v[122:125]
	v_mfma_f32_16x16x32_bf16 v[118:121], v[140:143], v[180:183], v[118:121]
	v_mfma_f32_16x16x32_bf16 v[114:117], v[148:151], v[180:183], v[114:117]
	v_mfma_f32_16x16x32_bf16 v[110:113], v[140:143], v[188:191], v[110:113]
	v_mfma_f32_16x16x32_bf16 v[106:109], v[148:151], v[188:191], v[106:109]
	v_mfma_f32_16x16x32_bf16 v[102:105], v[140:143], v[196:199], v[102:105]
	v_mfma_f32_16x16x32_bf16 v[98:101], v[148:151], v[196:199], v[98:101]
	s_setprio 0
	s_setprio 1
	v_mfma_f32_16x16x32_bf16 v[94:97], v[152:155], v[168:171], 0
	v_mfma_f32_16x16x32_bf16 v[90:93], v[160:163], v[168:171], 0
	v_mfma_f32_16x16x32_bf16 v[86:89], v[152:155], v[176:179], 0
	v_mfma_f32_16x16x32_bf16 v[82:85], v[160:163], v[176:179], 0
	v_mfma_f32_16x16x32_bf16 v[78:81], v[152:155], v[184:187], 0
	v_mfma_f32_16x16x32_bf16 v[74:77], v[160:163], v[184:187], 0
	v_mfma_f32_16x16x32_bf16 v[70:73], v[152:155], v[192:195], 0
	v_mfma_f32_16x16x32_bf16 v[66:69], v[160:163], v[192:195], 0
	v_mfma_f32_16x16x32_bf16 v[94:97], v[156:159], v[172:175], v[94:97]
	v_mfma_f32_16x16x32_bf16 v[90:93], v[164:167], v[172:175], v[90:93]
	v_mfma_f32_16x16x32_bf16 v[86:89], v[156:159], v[180:183], v[86:89]
	v_mfma_f32_16x16x32_bf16 v[82:85], v[164:167], v[180:183], v[82:85]
	v_mfma_f32_16x16x32_bf16 v[78:81], v[156:159], v[188:191], v[78:81]
	v_mfma_f32_16x16x32_bf16 v[74:77], v[164:167], v[188:191], v[74:77]
	v_mfma_f32_16x16x32_bf16 v[70:73], v[156:159], v[196:199], v[70:73]
	v_mfma_f32_16x16x32_bf16 v[66:69], v[164:167], v[196:199], v[66:69]
	s_setprio 0
	s_barrier
	s_add_i32 s89, s89, s37
	s_mov_b32 m0, s89
	ds_read_b128 v[168:171], v226 offset:16384
	ds_read_b128 v[172:175], v226 offset:17408
	ds_read_b128 v[176:179], v226 offset:18432
	ds_read_b128 v[180:183], v226 offset:19456
	ds_read_b128 v[184:187], v226 offset:20480
	ds_read_b128 v[188:191], v226 offset:21504
	ds_read_b128 v[192:195], v226 offset:22528
	ds_read_b128 v[196:199], v226 offset:23552
	global_load_lds_dwordx4 v16, s[28:29]
	s_add_i32 m0, s89, 0x2000
	s_add_u32 s90, s28, 0x80000
	s_addc_u32 s91, s29, 0
	s_add_i32 s89, s92, s37
	global_load_lds_dwordx4 v130, s[28:29]
	s_mov_b32 m0, s89
	v_lshl_add_u64 v[206:207], s[46:47], 0, v[130:131]
	global_load_lds_dwordx4 v16, s[90:91]
	s_add_i32 m0, s89, 0x2000
	s_nop 0
	global_load_lds_dwordx4 v130, s[90:91]
	v_lshl_add_u64 v[204:205], s[46:47], 0, v[16:17]
	s_mov_b32 m0, s43
	s_nop 0
	global_load_lds_dwordx4 v[204:205], off
	s_mov_b32 m0, s50
	s_nop 0
	global_load_lds_dwordx4 v[206:207], off
	s_waitcnt vmcnt(8)
	s_waitcnt lgkmcnt(0)
	s_barrier
	s_setprio 1
	s_waitcnt lgkmcnt(0)
	v_mfma_f32_16x16x32_bf16 v[62:65], v[136:139], v[168:171], 0
	v_mfma_f32_16x16x32_bf16 v[58:61], v[144:147], v[168:171], 0
	v_mfma_f32_16x16x32_bf16 v[54:57], v[136:139], v[176:179], 0
	v_mfma_f32_16x16x32_bf16 v[50:53], v[144:147], v[176:179], 0
	v_mfma_f32_16x16x32_bf16 v[46:49], v[136:139], v[184:187], 0
	v_mfma_f32_16x16x32_bf16 v[42:45], v[144:147], v[184:187], 0
	v_mfma_f32_16x16x32_bf16 v[38:41], v[136:139], v[192:195], 0
	v_mfma_f32_16x16x32_bf16 v[34:37], v[144:147], v[192:195], 0
	v_mfma_f32_16x16x32_bf16 v[62:65], v[140:143], v[172:175], v[62:65]
	v_mfma_f32_16x16x32_bf16 v[58:61], v[148:151], v[172:175], v[58:61]
	v_mfma_f32_16x16x32_bf16 v[54:57], v[140:143], v[180:183], v[54:57]
	v_mfma_f32_16x16x32_bf16 v[50:53], v[148:151], v[180:183], v[50:53]
	v_mfma_f32_16x16x32_bf16 v[46:49], v[140:143], v[188:191], v[46:49]
	v_mfma_f32_16x16x32_bf16 v[42:45], v[148:151], v[188:191], v[42:45]
	v_mfma_f32_16x16x32_bf16 v[38:41], v[140:143], v[196:199], v[38:41]
	v_mfma_f32_16x16x32_bf16 v[34:37], v[148:151], v[196:199], v[34:37]
	s_setprio 0
	s_setprio 1
	v_mfma_f32_16x16x32_bf16 v[30:33], v[152:155], v[168:171], 0
	v_mfma_f32_16x16x32_bf16 v[26:29], v[160:163], v[168:171], 0
	v_mfma_f32_16x16x32_bf16 v[22:25], v[152:155], v[176:179], 0
	v_mfma_f32_16x16x32_bf16 v[18:21], v[160:163], v[176:179], 0
	v_mfma_f32_16x16x32_bf16 v[12:15], v[152:155], v[184:187], 0
	v_mfma_f32_16x16x32_bf16 v[8:11], v[160:163], v[184:187], 0
	v_mfma_f32_16x16x32_bf16 v[4:7], v[152:155], v[192:195], 0
	v_mfma_f32_16x16x32_bf16 v[0:3], v[160:163], v[192:195], 0
	v_mfma_f32_16x16x32_bf16 v[30:33], v[156:159], v[172:175], v[30:33]
	v_mfma_f32_16x16x32_bf16 v[26:29], v[164:167], v[172:175], v[26:29]
	v_mfma_f32_16x16x32_bf16 v[22:25], v[156:159], v[180:183], v[22:25]
	v_mfma_f32_16x16x32_bf16 v[18:21], v[164:167], v[180:183], v[18:21]
	v_mfma_f32_16x16x32_bf16 v[12:15], v[156:159], v[188:191], v[12:15]
	v_mfma_f32_16x16x32_bf16 v[8:11], v[164:167], v[188:191], v[8:11]
	v_mfma_f32_16x16x32_bf16 v[4:7], v[156:159], v[196:199], v[4:7]
	v_mfma_f32_16x16x32_bf16 v[0:3], v[164:167], v[196:199], v[0:3]
	s_setprio 0
	s_barrier
	s_add_i32 s89, 0, 0x18000
	s_add_i32 s90, 0, 0x1c000
	v_add_u32_e32 v148, s89, v224
	v_add_u32_e32 v164, s90, v224
	ds_read_b128 v[136:139], v148
	ds_read_b128 v[140:143], v148 offset:1024
	ds_read_b128 v[144:147], v148 offset:2048
	ds_read_b128 v[148:151], v148 offset:3072
	ds_read_b128 v[152:155], v164
	ds_read_b128 v[156:159], v164 offset:1024
	ds_read_b128 v[160:163], v164 offset:2048
	ds_read_b128 v[164:167], v164 offset:3072
	s_add_u32 s46, s46, 0x80000
	s_addc_u32 s47, s47, 0
	s_mov_b32 m0, s51
	ds_read_b128 v[168:171], v226 offset:32768
	ds_read_b128 v[172:175], v226 offset:33792
	ds_read_b128 v[176:179], v226 offset:34816
	ds_read_b128 v[180:183], v226 offset:35840
	ds_read_b128 v[184:187], v226 offset:36864
	ds_read_b128 v[188:191], v226 offset:37888
	ds_read_b128 v[192:195], v226 offset:38912
	ds_read_b128 v[196:199], v226 offset:39936
	global_load_lds_dwordx4 v16, s[46:47]
	s_mov_b32 m0, s52
	s_nop 0
	global_load_lds_dwordx4 v130, s[46:47]
	s_waitcnt vmcnt(8)
	s_waitcnt lgkmcnt(0)
	s_barrier
	s_setprio 1
	s_waitcnt lgkmcnt(0)
	v_mfma_f32_16x16x32_bf16 v[126:129], v[136:139], v[168:171], v[126:129]
	v_mfma_f32_16x16x32_bf16 v[122:125], v[144:147], v[168:171], v[122:125]
	v_mfma_f32_16x16x32_bf16 v[118:121], v[136:139], v[176:179], v[118:121]
	v_mfma_f32_16x16x32_bf16 v[114:117], v[144:147], v[176:179], v[114:117]
	v_mfma_f32_16x16x32_bf16 v[110:113], v[136:139], v[184:187], v[110:113]
	v_mfma_f32_16x16x32_bf16 v[106:109], v[144:147], v[184:187], v[106:109]
	v_mfma_f32_16x16x32_bf16 v[102:105], v[136:139], v[192:195], v[102:105]
	v_mfma_f32_16x16x32_bf16 v[98:101], v[144:147], v[192:195], v[98:101]
	v_mfma_f32_16x16x32_bf16 v[126:129], v[140:143], v[172:175], v[126:129]
	v_mfma_f32_16x16x32_bf16 v[122:125], v[148:151], v[172:175], v[122:125]
	v_mfma_f32_16x16x32_bf16 v[118:121], v[140:143], v[180:183], v[118:121]
	v_mfma_f32_16x16x32_bf16 v[114:117], v[148:151], v[180:183], v[114:117]
	v_mfma_f32_16x16x32_bf16 v[110:113], v[140:143], v[188:191], v[110:113]
	v_mfma_f32_16x16x32_bf16 v[106:109], v[148:151], v[188:191], v[106:109]
	v_mfma_f32_16x16x32_bf16 v[102:105], v[140:143], v[196:199], v[102:105]
	v_mfma_f32_16x16x32_bf16 v[98:101], v[148:151], v[196:199], v[98:101]
	s_setprio 0
	s_setprio 1
	v_mfma_f32_16x16x32_bf16 v[94:97], v[152:155], v[168:171], v[94:97]
	v_mfma_f32_16x16x32_bf16 v[90:93], v[160:163], v[168:171], v[90:93]
	v_mfma_f32_16x16x32_bf16 v[86:89], v[152:155], v[176:179], v[86:89]
	v_mfma_f32_16x16x32_bf16 v[82:85], v[160:163], v[176:179], v[82:85]
	v_mfma_f32_16x16x32_bf16 v[78:81], v[152:155], v[184:187], v[78:81]
	v_mfma_f32_16x16x32_bf16 v[74:77], v[160:163], v[184:187], v[74:77]
	v_mfma_f32_16x16x32_bf16 v[70:73], v[152:155], v[192:195], v[70:73]
	v_mfma_f32_16x16x32_bf16 v[66:69], v[160:163], v[192:195], v[66:69]
	v_mfma_f32_16x16x32_bf16 v[94:97], v[156:159], v[172:175], v[94:97]
	v_mfma_f32_16x16x32_bf16 v[90:93], v[164:167], v[172:175], v[90:93]
	v_mfma_f32_16x16x32_bf16 v[86:89], v[156:159], v[180:183], v[86:89]
	v_mfma_f32_16x16x32_bf16 v[82:85], v[164:167], v[180:183], v[82:85]
	v_mfma_f32_16x16x32_bf16 v[78:81], v[156:159], v[188:191], v[78:81]
	v_mfma_f32_16x16x32_bf16 v[74:77], v[164:167], v[188:191], v[74:77]
	v_mfma_f32_16x16x32_bf16 v[70:73], v[156:159], v[196:199], v[70:73]
	v_mfma_f32_16x16x32_bf16 v[66:69], v[164:167], v[196:199], v[66:69]
	s_setprio 0
	s_barrier
	s_add_i32 s46, s89, s37
	s_add_u32 s28, s28, 0x80
	s_addc_u32 s29, s29, 0
	s_mov_b32 m0, s46
	ds_read_b128 v[168:171], v226 offset:49152
	ds_read_b128 v[172:175], v226 offset:50176
	ds_read_b128 v[176:179], v226 offset:51200
	ds_read_b128 v[180:183], v226 offset:52224
	ds_read_b128 v[184:187], v226 offset:53248
	ds_read_b128 v[188:191], v226 offset:54272
	ds_read_b128 v[192:195], v226 offset:55296
	ds_read_b128 v[196:199], v226 offset:56320
	global_load_lds_dwordx4 v16, s[28:29]
	s_add_i32 m0, s46, 0x2000
	s_add_i32 s46, s90, s37
	global_load_lds_dwordx4 v130, s[28:29]
	s_add_u32 s28, s28, 0x80000
	s_addc_u32 s29, s29, 0
	s_mov_b32 m0, s46
	s_nop 0
	global_load_lds_dwordx4 v16, s[28:29]
	s_add_i32 m0, s46, 0x2000
	s_nop 0
	global_load_lds_dwordx4 v130, s[28:29]
	v_lshl_add_u64 v[200:201], v[204:205], 0, s[34:35]
	s_mov_b32 m0, s53
	s_nop 0
	global_load_lds_dwordx4 v[200:201], off
	v_lshl_add_u64 v[200:201], v[206:207], 0, s[34:35]
	s_mov_b32 m0, s58
	s_nop 0
	global_load_lds_dwordx4 v[200:201], off
	s_waitcnt vmcnt(8)
	s_waitcnt lgkmcnt(0)
	s_barrier
	s_setprio 1
	s_waitcnt lgkmcnt(0)
	v_mfma_f32_16x16x32_bf16 v[62:65], v[136:139], v[168:171], v[62:65]
	v_mfma_f32_16x16x32_bf16 v[58:61], v[144:147], v[168:171], v[58:61]
	v_mfma_f32_16x16x32_bf16 v[54:57], v[136:139], v[176:179], v[54:57]
	v_mfma_f32_16x16x32_bf16 v[50:53], v[144:147], v[176:179], v[50:53]
	v_mfma_f32_16x16x32_bf16 v[46:49], v[136:139], v[184:187], v[46:49]
	v_mfma_f32_16x16x32_bf16 v[42:45], v[144:147], v[184:187], v[42:45]
	v_mfma_f32_16x16x32_bf16 v[38:41], v[136:139], v[192:195], v[38:41]
	v_mfma_f32_16x16x32_bf16 v[34:37], v[144:147], v[192:195], v[34:37]
	v_mfma_f32_16x16x32_bf16 v[62:65], v[140:143], v[172:175], v[62:65]
	v_mfma_f32_16x16x32_bf16 v[58:61], v[148:151], v[172:175], v[58:61]
	v_mfma_f32_16x16x32_bf16 v[54:57], v[140:143], v[180:183], v[54:57]
	v_mfma_f32_16x16x32_bf16 v[50:53], v[148:151], v[180:183], v[50:53]
	v_mfma_f32_16x16x32_bf16 v[46:49], v[140:143], v[188:191], v[46:49]
	v_mfma_f32_16x16x32_bf16 v[42:45], v[148:151], v[188:191], v[42:45]
	v_mfma_f32_16x16x32_bf16 v[38:41], v[140:143], v[196:199], v[38:41]
	v_mfma_f32_16x16x32_bf16 v[34:37], v[148:151], v[196:199], v[34:37]
	s_setprio 0
	s_setprio 1
	v_mfma_f32_16x16x32_bf16 v[30:33], v[152:155], v[168:171], v[30:33]
	v_mfma_f32_16x16x32_bf16 v[26:29], v[160:163], v[168:171], v[26:29]
	v_mfma_f32_16x16x32_bf16 v[22:25], v[152:155], v[176:179], v[22:25]
	v_mfma_f32_16x16x32_bf16 v[18:21], v[160:163], v[176:179], v[18:21]
	v_mfma_f32_16x16x32_bf16 v[12:15], v[152:155], v[184:187], v[12:15]
	v_mfma_f32_16x16x32_bf16 v[8:11], v[160:163], v[184:187], v[8:11]
	v_mfma_f32_16x16x32_bf16 v[4:7], v[152:155], v[192:195], v[4:7]
	v_mfma_f32_16x16x32_bf16 v[0:3], v[160:163], v[192:195], v[0:3]
	v_mfma_f32_16x16x32_bf16 v[30:33], v[156:159], v[172:175], v[30:33]
	v_mfma_f32_16x16x32_bf16 v[26:29], v[164:167], v[172:175], v[26:29]
	v_mfma_f32_16x16x32_bf16 v[22:25], v[156:159], v[180:183], v[22:25]
	v_mfma_f32_16x16x32_bf16 v[18:21], v[164:167], v[180:183], v[18:21]
	v_mfma_f32_16x16x32_bf16 v[12:15], v[156:159], v[188:191], v[12:15]
	v_mfma_f32_16x16x32_bf16 v[8:11], v[164:167], v[188:191], v[8:11]
	v_mfma_f32_16x16x32_bf16 v[4:7], v[156:159], v[196:199], v[4:7]
	v_mfma_f32_16x16x32_bf16 v[0:3], v[164:167], v[196:199], v[0:3]
	s_setprio 0
	s_barrier
	s_add_i32 s88, s88, 2
	s_add_u32 s44, s44, 0x100
	s_addc_u32 s45, s45, 0
	s_add_u32 s86, s86, 0x100
	s_addc_u32 s87, s87, 0
	s_cmp_gt_u32 s88, 29
	s_cbranch_scc1 .Lpz_F_exit

.LBB0_786:
	s_ashr_i32 s43, s42, 31
	s_lshl_b64 s[28:29], s[42:43], 20
	s_add_u32 s44, s72, s28
	s_addc_u32 s45, s73, s29
	s_and_b64 s[28:29], s[38:39], exec
	s_cselect_b32 s43, s45, s51
	s_cselect_b32 s91, s44, s50
	s_ashr_i32 s41, s40, 31
	s_lshl_b64 s[28:29], s[40:41], 20
	v_readlane_b32 s41, v255, 14
	s_add_u32 s46, s41, s28
	v_readlane_b32 s28, v255, 15
	s_addc_u32 s47, s28, s29
	s_and_b64 s[28:29], s[38:39], exec
	s_cselect_b32 s41, s47, s53
	s_cselect_b32 vcc_lo, s46, s52
	s_add_u32 s50, s50, 0x80080
	s_addc_u32 s51, s51, 0
	s_add_u32 vcc_hi, s52, 0x100
	s_addc_u32 s92, s53, 0
	s_mov_b32 s93, -2
	s_add_u32 s28, s50, 0xfff80080
	s_addc_u32 s29, s51, -1
	s_add_i32 s94, 0, 0x10000
	s_cmp_eq_u32 s93, 28
	s_cselect_b32 s53, s43, s29
	s_cselect_b32 s52, s91, s28
	s_cselect_b32 s29, s41, s92
	s_cselect_b32 s28, vcc_lo, vcc_hi
	s_add_i32 s96, 0, 0x14000
	s_waitcnt vmcnt(0)
	v_add_u32_e32 v142, s94, v207
	v_add_u32_e32 v158, s96, v207
	ds_read_b128 v[130:133], v142
	ds_read_b128 v[134:137], v142 offset:1024
	ds_read_b128 v[138:141], v142 offset:2048
	ds_read_b128 v[142:145], v142 offset:3072
	ds_read_b128 v[146:149], v158
	ds_read_b128 v[150:153], v158 offset:1024
	ds_read_b128 v[154:157], v158 offset:2048
	ds_read_b128 v[158:161], v158 offset:3072
	s_add_i32 m0, s59, 0xc000
	ds_read_b128 v[162:165], v224
	ds_read_b128 v[166:169], v224 offset:1024
	ds_read_b128 v[170:173], v224 offset:2048
	ds_read_b128 v[174:177], v224 offset:3072
	ds_read_b128 v[178:181], v224 offset:4096
	ds_read_b128 v[182:185], v224 offset:5120
	ds_read_b128 v[196:199], v224 offset:6144
	ds_read_b128 v[200:203], v224 offset:7168
	global_load_lds_dwordx4 v192, s[50:51]
	s_add_i32 m0, s59, 0xe000
	s_nop 0
	global_load_lds_dwordx4 v194, s[50:51]
	s_waitcnt vmcnt(8)
	s_waitcnt lgkmcnt(0)
	s_barrier
	s_setprio 1
	s_waitcnt lgkmcnt(0)
	v_mfma_f32_16x16x32_bf16 v[126:129], v[130:133], v[162:165], 0
	v_mfma_f32_16x16x32_bf16 v[122:125], v[138:141], v[162:165], 0
	v_mfma_f32_16x16x32_bf16 v[114:117], v[130:133], v[170:173], 0
	v_mfma_f32_16x16x32_bf16 v[106:109], v[138:141], v[170:173], 0
	v_mfma_f32_16x16x32_bf16 v[98:101], v[130:133], v[178:181], 0
	v_mfma_f32_16x16x32_bf16 v[90:93], v[138:141], v[178:181], 0
	v_mfma_f32_16x16x32_bf16 v[82:85], v[130:133], v[196:199], 0
	v_mfma_f32_16x16x32_bf16 v[74:77], v[138:141], v[196:199], 0
	v_mfma_f32_16x16x32_bf16 v[126:129], v[134:137], v[166:169], v[126:129]
	v_mfma_f32_16x16x32_bf16 v[122:125], v[142:145], v[166:169], v[122:125]
	v_mfma_f32_16x16x32_bf16 v[114:117], v[134:137], v[174:177], v[114:117]
	v_mfma_f32_16x16x32_bf16 v[106:109], v[142:145], v[174:177], v[106:109]
	v_mfma_f32_16x16x32_bf16 v[98:101], v[134:137], v[182:185], v[98:101]
	v_mfma_f32_16x16x32_bf16 v[90:93], v[142:145], v[182:185], v[90:93]
	v_mfma_f32_16x16x32_bf16 v[82:85], v[134:137], v[200:203], v[82:85]
	v_mfma_f32_16x16x32_bf16 v[74:77], v[142:145], v[200:203], v[74:77]
	s_setprio 0
	s_setprio 1
	v_mfma_f32_16x16x32_bf16 v[118:121], v[146:149], v[162:165], 0
	v_mfma_f32_16x16x32_bf16 v[110:113], v[154:157], v[162:165], 0
	v_mfma_f32_16x16x32_bf16 v[102:105], v[146:149], v[170:173], 0
	v_mfma_f32_16x16x32_bf16 v[94:97], v[154:157], v[170:173], 0
	v_mfma_f32_16x16x32_bf16 v[86:89], v[146:149], v[178:181], 0
	v_mfma_f32_16x16x32_bf16 v[78:81], v[154:157], v[178:181], 0
	v_mfma_f32_16x16x32_bf16 v[70:73], v[146:149], v[196:199], 0
	v_mfma_f32_16x16x32_bf16 v[66:69], v[154:157], v[196:199], 0
	v_mfma_f32_16x16x32_bf16 v[118:121], v[150:153], v[166:169], v[118:121]
	v_mfma_f32_16x16x32_bf16 v[110:113], v[158:161], v[166:169], v[110:113]
	v_mfma_f32_16x16x32_bf16 v[102:105], v[150:153], v[174:177], v[102:105]
	v_mfma_f32_16x16x32_bf16 v[94:97], v[158:161], v[174:177], v[94:97]
	v_mfma_f32_16x16x32_bf16 v[86:89], v[150:153], v[182:185], v[86:89]
	v_mfma_f32_16x16x32_bf16 v[78:81], v[158:161], v[182:185], v[78:81]
	v_mfma_f32_16x16x32_bf16 v[70:73], v[150:153], v[200:203], v[70:73]
	v_mfma_f32_16x16x32_bf16 v[66:69], v[158:161], v[200:203], v[66:69]
	s_setprio 0
	s_barrier
	s_add_i32 s94, s94, s37
	s_mov_b32 m0, s94
	ds_read_b128 v[162:165], v224 offset:16384
	ds_read_b128 v[166:169], v224 offset:17408
	ds_read_b128 v[170:173], v224 offset:18432
	ds_read_b128 v[174:177], v224 offset:19456
	ds_read_b128 v[178:181], v224 offset:20480
	ds_read_b128 v[182:185], v224 offset:21504
	ds_read_b128 v[196:199], v224 offset:22528
	ds_read_b128 v[200:203], v224 offset:23552
	global_load_lds_dwordx4 v16, s[28:29]
	s_add_i32 m0, s94, 0x2000
	s_add_u32 s94, s28, 0x80000
	s_addc_u32 s95, s29, 0
	s_add_i32 s96, s96, s37
	global_load_lds_dwordx4 v186, s[28:29]
	s_mov_b32 m0, s96
	v_lshl_add_u64 v[230:231], s[52:53], 0, v[188:189]
	global_load_lds_dwordx4 v16, s[94:95]
	s_add_i32 m0, s96, 0x2000
	s_nop 0
	global_load_lds_dwordx4 v186, s[94:95]
	v_lshl_add_u64 v[228:229], s[52:53], 0, v[190:191]
	s_mov_b32 m0, s59
	s_nop 0
	global_load_lds_dwordx4 v[228:229], off
	s_mov_b32 m0, s83
	s_nop 0
	global_load_lds_dwordx4 v[230:231], off
	s_waitcnt vmcnt(8)
	s_waitcnt lgkmcnt(0)
	s_barrier
	s_setprio 1
	s_waitcnt lgkmcnt(0)
	v_mfma_f32_16x16x32_bf16 v[62:65], v[130:133], v[162:165], 0
	v_mfma_f32_16x16x32_bf16 v[58:61], v[138:141], v[162:165], 0
	v_mfma_f32_16x16x32_bf16 v[50:53], v[130:133], v[170:173], 0
	v_mfma_f32_16x16x32_bf16 v[42:45], v[138:141], v[170:173], 0
	v_mfma_f32_16x16x32_bf16 v[34:37], v[130:133], v[178:181], 0
	v_mfma_f32_16x16x32_bf16 v[26:29], v[138:141], v[178:181], 0
	v_mfma_f32_16x16x32_bf16 v[18:21], v[130:133], v[196:199], 0
	v_mfma_f32_16x16x32_bf16 v[8:11], v[138:141], v[196:199], 0
	v_mfma_f32_16x16x32_bf16 v[62:65], v[134:137], v[166:169], v[62:65]
	v_mfma_f32_16x16x32_bf16 v[58:61], v[142:145], v[166:169], v[58:61]
	v_mfma_f32_16x16x32_bf16 v[50:53], v[134:137], v[174:177], v[50:53]
	v_mfma_f32_16x16x32_bf16 v[42:45], v[142:145], v[174:177], v[42:45]
	v_mfma_f32_16x16x32_bf16 v[34:37], v[134:137], v[182:185], v[34:37]
	v_mfma_f32_16x16x32_bf16 v[26:29], v[142:145], v[182:185], v[26:29]
	v_mfma_f32_16x16x32_bf16 v[18:21], v[134:137], v[200:203], v[18:21]
	v_mfma_f32_16x16x32_bf16 v[8:11], v[142:145], v[200:203], v[8:11]
	s_setprio 0
	s_setprio 1
	v_mfma_f32_16x16x32_bf16 v[54:57], v[146:149], v[162:165], 0
	v_mfma_f32_16x16x32_bf16 v[46:49], v[154:157], v[162:165], 0
	v_mfma_f32_16x16x32_bf16 v[38:41], v[146:149], v[170:173], 0
	v_mfma_f32_16x16x32_bf16 v[30:33], v[154:157], v[170:173], 0
	v_mfma_f32_16x16x32_bf16 v[22:25], v[146:149], v[178:181], 0
	v_mfma_f32_16x16x32_bf16 v[12:15], v[154:157], v[178:181], 0
	v_mfma_f32_16x16x32_bf16 v[4:7], v[146:149], v[196:199], 0
	v_mfma_f32_16x16x32_bf16 v[0:3], v[154:157], v[196:199], 0
	v_mfma_f32_16x16x32_bf16 v[54:57], v[150:153], v[166:169], v[54:57]
	v_mfma_f32_16x16x32_bf16 v[46:49], v[158:161], v[166:169], v[46:49]
	v_mfma_f32_16x16x32_bf16 v[38:41], v[150:153], v[174:177], v[38:41]
	v_mfma_f32_16x16x32_bf16 v[30:33], v[158:161], v[174:177], v[30:33]
	v_mfma_f32_16x16x32_bf16 v[22:25], v[150:153], v[182:185], v[22:25]
	v_mfma_f32_16x16x32_bf16 v[12:15], v[158:161], v[182:185], v[12:15]
	v_mfma_f32_16x16x32_bf16 v[4:7], v[150:153], v[200:203], v[4:7]
	v_mfma_f32_16x16x32_bf16 v[0:3], v[158:161], v[200:203], v[0:3]
	s_setprio 0
	s_barrier
	s_add_i32 s94, 0, 0x18000
	s_add_i32 s95, 0, 0x1c000
	v_add_u32_e32 v142, s94, v207
	v_add_u32_e32 v158, s95, v207
	ds_read_b128 v[130:133], v142
	ds_read_b128 v[134:137], v142 offset:1024
	ds_read_b128 v[138:141], v142 offset:2048
	ds_read_b128 v[142:145], v142 offset:3072
	ds_read_b128 v[146:149], v158
	ds_read_b128 v[150:153], v158 offset:1024
	ds_read_b128 v[154:157], v158 offset:2048
	ds_read_b128 v[158:161], v158 offset:3072
	s_add_u32 s52, s52, 0x80000
	s_addc_u32 s53, s53, 0
	s_mov_b32 m0, s84
	ds_read_b128 v[162:165], v224 offset:32768
	ds_read_b128 v[166:169], v224 offset:33792
	ds_read_b128 v[170:173], v224 offset:34816
	ds_read_b128 v[174:177], v224 offset:35840
	ds_read_b128 v[178:181], v224 offset:36864
	ds_read_b128 v[182:185], v224 offset:37888
	ds_read_b128 v[196:199], v224 offset:38912
	ds_read_b128 v[200:203], v224 offset:39936
	global_load_lds_dwordx4 v190, s[52:53]
	s_mov_b32 m0, s85
	s_nop 0
	global_load_lds_dwordx4 v188, s[52:53]
	s_waitcnt vmcnt(8)
	s_waitcnt lgkmcnt(0)
	s_barrier
	s_setprio 1
	s_waitcnt lgkmcnt(0)
	v_mfma_f32_16x16x32_bf16 v[126:129], v[130:133], v[162:165], v[126:129]
	v_mfma_f32_16x16x32_bf16 v[122:125], v[138:141], v[162:165], v[122:125]
	v_mfma_f32_16x16x32_bf16 v[114:117], v[130:133], v[170:173], v[114:117]
	v_mfma_f32_16x16x32_bf16 v[106:109], v[138:141], v[170:173], v[106:109]
	v_mfma_f32_16x16x32_bf16 v[98:101], v[130:133], v[178:181], v[98:101]
	v_mfma_f32_16x16x32_bf16 v[90:93], v[138:141], v[178:181], v[90:93]
	v_mfma_f32_16x16x32_bf16 v[82:85], v[130:133], v[196:199], v[82:85]
	v_mfma_f32_16x16x32_bf16 v[74:77], v[138:141], v[196:199], v[74:77]
	v_mfma_f32_16x16x32_bf16 v[126:129], v[134:137], v[166:169], v[126:129]
	v_mfma_f32_16x16x32_bf16 v[122:125], v[142:145], v[166:169], v[122:125]
	v_mfma_f32_16x16x32_bf16 v[114:117], v[134:137], v[174:177], v[114:117]
	v_mfma_f32_16x16x32_bf16 v[106:109], v[142:145], v[174:177], v[106:109]
	v_mfma_f32_16x16x32_bf16 v[98:101], v[134:137], v[182:185], v[98:101]
	v_mfma_f32_16x16x32_bf16 v[90:93], v[142:145], v[182:185], v[90:93]
	v_mfma_f32_16x16x32_bf16 v[82:85], v[134:137], v[200:203], v[82:85]
	v_mfma_f32_16x16x32_bf16 v[74:77], v[142:145], v[200:203], v[74:77]
	s_setprio 0
	s_setprio 1
	v_mfma_f32_16x16x32_bf16 v[118:121], v[146:149], v[162:165], v[118:121]
	v_mfma_f32_16x16x32_bf16 v[110:113], v[154:157], v[162:165], v[110:113]
	v_mfma_f32_16x16x32_bf16 v[102:105], v[146:149], v[170:173], v[102:105]
	v_mfma_f32_16x16x32_bf16 v[94:97], v[154:157], v[170:173], v[94:97]
	v_mfma_f32_16x16x32_bf16 v[86:89], v[146:149], v[178:181], v[86:89]
	v_mfma_f32_16x16x32_bf16 v[78:81], v[154:157], v[178:181], v[78:81]
	v_mfma_f32_16x16x32_bf16 v[70:73], v[146:149], v[196:199], v[70:73]
	v_mfma_f32_16x16x32_bf16 v[66:69], v[154:157], v[196:199], v[66:69]
	v_mfma_f32_16x16x32_bf16 v[118:121], v[150:153], v[166:169], v[118:121]
	v_mfma_f32_16x16x32_bf16 v[110:113], v[158:161], v[166:169], v[110:113]
	v_mfma_f32_16x16x32_bf16 v[102:105], v[150:153], v[174:177], v[102:105]
	v_mfma_f32_16x16x32_bf16 v[94:97], v[158:161], v[174:177], v[94:97]
	v_mfma_f32_16x16x32_bf16 v[86:89], v[150:153], v[182:185], v[86:89]
	v_mfma_f32_16x16x32_bf16 v[78:81], v[158:161], v[182:185], v[78:81]
	v_mfma_f32_16x16x32_bf16 v[70:73], v[150:153], v[200:203], v[70:73]
	v_mfma_f32_16x16x32_bf16 v[66:69], v[158:161], v[200:203], v[66:69]
	s_setprio 0
	s_barrier
	s_add_i32 s52, s94, s37
	s_add_u32 s28, s28, 0x80
	s_addc_u32 s29, s29, 0
	s_mov_b32 m0, s52
	ds_read_b128 v[162:165], v224 offset:49152
	ds_read_b128 v[166:169], v224 offset:50176
	ds_read_b128 v[170:173], v224 offset:51200
	ds_read_b128 v[174:177], v224 offset:52224
	ds_read_b128 v[178:181], v224 offset:53248
	ds_read_b128 v[182:185], v224 offset:54272
	ds_read_b128 v[196:199], v224 offset:55296
	ds_read_b128 v[200:203], v224 offset:56320
	global_load_lds_dwordx4 v16, s[28:29]
	s_add_i32 m0, s52, 0x2000
	s_add_i32 s52, s95, s37
	global_load_lds_dwordx4 v186, s[28:29]
	s_add_u32 s28, s28, 0x80000
	s_addc_u32 s29, s29, 0
	s_mov_b32 m0, s52
	s_nop 0
	global_load_lds_dwordx4 v16, s[28:29]
	s_add_i32 m0, s52, 0x2000
	s_nop 0
	global_load_lds_dwordx4 v186, s[28:29]
	v_lshl_add_u64 v[204:205], v[228:229], 0, s[34:35]
	s_mov_b32 m0, s88
	s_nop 0
	global_load_lds_dwordx4 v[204:205], off
	v_lshl_add_u64 v[204:205], v[230:231], 0, s[34:35]
	s_mov_b32 m0, s89
	s_nop 0
	global_load_lds_dwordx4 v[204:205], off
	s_waitcnt vmcnt(8)
	s_waitcnt lgkmcnt(0)
	s_barrier
	s_setprio 1
	s_waitcnt lgkmcnt(0)
	v_mfma_f32_16x16x32_bf16 v[62:65], v[130:133], v[162:165], v[62:65]
	v_mfma_f32_16x16x32_bf16 v[58:61], v[138:141], v[162:165], v[58:61]
	v_mfma_f32_16x16x32_bf16 v[50:53], v[130:133], v[170:173], v[50:53]
	v_mfma_f32_16x16x32_bf16 v[42:45], v[138:141], v[170:173], v[42:45]
	v_mfma_f32_16x16x32_bf16 v[34:37], v[130:133], v[178:181], v[34:37]
	v_mfma_f32_16x16x32_bf16 v[26:29], v[138:141], v[178:181], v[26:29]
	v_mfma_f32_16x16x32_bf16 v[18:21], v[130:133], v[196:199], v[18:21]
	v_mfma_f32_16x16x32_bf16 v[8:11], v[138:141], v[196:199], v[8:11]
	v_mfma_f32_16x16x32_bf16 v[62:65], v[134:137], v[166:169], v[62:65]
	v_mfma_f32_16x16x32_bf16 v[58:61], v[142:145], v[166:169], v[58:61]
	v_mfma_f32_16x16x32_bf16 v[50:53], v[134:137], v[174:177], v[50:53]
	v_mfma_f32_16x16x32_bf16 v[42:45], v[142:145], v[174:177], v[42:45]
	v_mfma_f32_16x16x32_bf16 v[34:37], v[134:137], v[182:185], v[34:37]
	v_mfma_f32_16x16x32_bf16 v[26:29], v[142:145], v[182:185], v[26:29]
	v_mfma_f32_16x16x32_bf16 v[18:21], v[134:137], v[200:203], v[18:21]
	v_mfma_f32_16x16x32_bf16 v[8:11], v[142:145], v[200:203], v[8:11]
	s_setprio 0
	s_setprio 1
	v_mfma_f32_16x16x32_bf16 v[54:57], v[146:149], v[162:165], v[54:57]
	v_mfma_f32_16x16x32_bf16 v[46:49], v[154:157], v[162:165], v[46:49]
	v_mfma_f32_16x16x32_bf16 v[38:41], v[146:149], v[170:173], v[38:41]
	v_mfma_f32_16x16x32_bf16 v[30:33], v[154:157], v[170:173], v[30:33]
	v_mfma_f32_16x16x32_bf16 v[22:25], v[146:149], v[178:181], v[22:25]
	v_mfma_f32_16x16x32_bf16 v[12:15], v[154:157], v[178:181], v[12:15]
	v_mfma_f32_16x16x32_bf16 v[4:7], v[146:149], v[196:199], v[4:7]
	v_mfma_f32_16x16x32_bf16 v[0:3], v[154:157], v[196:199], v[0:3]
	v_mfma_f32_16x16x32_bf16 v[54:57], v[150:153], v[166:169], v[54:57]
	v_mfma_f32_16x16x32_bf16 v[46:49], v[158:161], v[166:169], v[46:49]
	v_mfma_f32_16x16x32_bf16 v[38:41], v[150:153], v[174:177], v[38:41]
	v_mfma_f32_16x16x32_bf16 v[30:33], v[158:161], v[174:177], v[30:33]
	v_mfma_f32_16x16x32_bf16 v[22:25], v[150:153], v[182:185], v[22:25]
	v_mfma_f32_16x16x32_bf16 v[12:15], v[158:161], v[182:185], v[12:15]
	v_mfma_f32_16x16x32_bf16 v[4:7], v[150:153], v[200:203], v[4:7]
	v_mfma_f32_16x16x32_bf16 v[0:3], v[158:161], v[200:203], v[0:3]
	s_setprio 0
	s_barrier
	s_add_i32 s93, s93, 2
	s_add_u32 s50, s50, 0x100
	s_addc_u32 s51, s51, 0
	s_add_u32 vcc_hi, vcc_hi, 0x100
	s_addc_u32 s92, s92, 0
	s_cmp_gt_u32 s93, 29
	s_cbranch_scc1 .Lpz_G_exit

.LBB0_919:
	s_ashr_i32 s27, s26, 31
	s_lshl_b64 s[28:29], s[26:27], 20
	s_add_u32 s40, s68, s28
	s_addc_u32 s41, s69, s29
	s_and_b64 s[28:29], s[38:39], exec
	s_cselect_b32 s27, s41, s47
	s_cselect_b32 s86, s40, s46
	s_ashr_i32 s23, s22, 31
	s_lshl_b64 s[28:29], s[22:23], 20
	v_readlane_b32 s23, v255, 16
	s_add_u32 s42, s23, s28
	v_readlane_b32 s23, v255, 17
	s_addc_u32 s43, s23, s29
	s_and_b64 s[28:29], s[38:39], exec
	s_cselect_b32 s23, s43, s49
	s_cselect_b32 s87, s42, s48
	s_add_u32 s46, s46, 0x80080
	s_addc_u32 s47, s47, 0
	s_add_u32 s88, s48, 0x100
	s_addc_u32 s89, s49, 0
	s_mov_b32 s90, -2
	s_add_u32 s28, s46, 0xfff80080
	s_addc_u32 s29, s47, -1
	s_add_i32 s91, 0, 0x10000
	s_cmp_eq_u32 s90, 28
	s_cselect_b32 s49, s27, s29
	s_cselect_b32 s48, s86, s28
	s_cselect_b32 s29, s23, s89
	s_cselect_b32 s28, s87, s88
	s_add_i32 s94, 0, 0x14000
	v_add_u32_e32 v156, s91, v141
	v_add_u32_e32 v172, s94, v141
	ds_read_b128 v[144:147], v156
	ds_read_b128 v[148:151], v156 offset:1024
	ds_read_b128 v[152:155], v156 offset:2048
	ds_read_b128 v[156:159], v156 offset:3072
	ds_read_b128 v[160:163], v172
	ds_read_b128 v[164:167], v172 offset:1024
	ds_read_b128 v[168:171], v172 offset:2048
	ds_read_b128 v[172:175], v172 offset:3072
	s_add_i32 m0, s45, 0xc000
	ds_read_b128 v[176:179], v143
	ds_read_b128 v[180:183], v143 offset:1024
	ds_read_b128 v[184:187], v143 offset:2048
	ds_read_b128 v[188:191], v143 offset:3072
	ds_read_b128 v[192:195], v143 offset:4096
	ds_read_b128 v[196:199], v143 offset:5120
	ds_read_b128 v[200:203], v143 offset:6144
	ds_read_b128 v[204:207], v143 offset:7168
	global_load_lds_dwordx4 v136, s[46:47]
	s_add_i32 m0, s45, 0xe000
	s_nop 0
	global_load_lds_dwordx4 v138, s[46:47]
	s_waitcnt vmcnt(8)
	s_waitcnt lgkmcnt(0)
	s_barrier
	s_setprio 1
	s_waitcnt lgkmcnt(0)
	v_mfma_f32_16x16x32_bf16 v[126:129], v[144:147], v[176:179], 0
	v_mfma_f32_16x16x32_bf16 v[118:121], v[152:155], v[176:179], 0
	v_mfma_f32_16x16x32_bf16 v[110:113], v[144:147], v[184:187], 0
	v_mfma_f32_16x16x32_bf16 v[102:105], v[152:155], v[184:187], 0
	v_mfma_f32_16x16x32_bf16 v[94:97], v[144:147], v[192:195], 0
	v_mfma_f32_16x16x32_bf16 v[86:89], v[152:155], v[192:195], 0
	v_mfma_f32_16x16x32_bf16 v[78:81], v[144:147], v[200:203], 0
	v_mfma_f32_16x16x32_bf16 v[70:73], v[152:155], v[200:203], 0
	v_mfma_f32_16x16x32_bf16 v[126:129], v[148:151], v[180:183], v[126:129]
	v_mfma_f32_16x16x32_bf16 v[118:121], v[156:159], v[180:183], v[118:121]
	v_mfma_f32_16x16x32_bf16 v[110:113], v[148:151], v[188:191], v[110:113]
	v_mfma_f32_16x16x32_bf16 v[102:105], v[156:159], v[188:191], v[102:105]
	v_mfma_f32_16x16x32_bf16 v[94:97], v[148:151], v[196:199], v[94:97]
	v_mfma_f32_16x16x32_bf16 v[86:89], v[156:159], v[196:199], v[86:89]
	v_mfma_f32_16x16x32_bf16 v[78:81], v[148:151], v[204:207], v[78:81]
	v_mfma_f32_16x16x32_bf16 v[70:73], v[156:159], v[204:207], v[70:73]
	s_setprio 0
	s_setprio 1
	v_mfma_f32_16x16x32_bf16 v[122:125], v[160:163], v[176:179], 0
	v_mfma_f32_16x16x32_bf16 v[114:117], v[168:171], v[176:179], 0
	v_mfma_f32_16x16x32_bf16 v[106:109], v[160:163], v[184:187], 0
	v_mfma_f32_16x16x32_bf16 v[98:101], v[168:171], v[184:187], 0
	v_mfma_f32_16x16x32_bf16 v[90:93], v[160:163], v[192:195], 0
	v_mfma_f32_16x16x32_bf16 v[82:85], v[168:171], v[192:195], 0
	v_mfma_f32_16x16x32_bf16 v[74:77], v[160:163], v[200:203], 0
	v_mfma_f32_16x16x32_bf16 v[66:69], v[168:171], v[200:203], 0
	v_mfma_f32_16x16x32_bf16 v[122:125], v[164:167], v[180:183], v[122:125]
	v_mfma_f32_16x16x32_bf16 v[114:117], v[172:175], v[180:183], v[114:117]
	v_mfma_f32_16x16x32_bf16 v[106:109], v[164:167], v[188:191], v[106:109]
	v_mfma_f32_16x16x32_bf16 v[98:101], v[172:175], v[188:191], v[98:101]
	v_mfma_f32_16x16x32_bf16 v[90:93], v[164:167], v[196:199], v[90:93]
	v_mfma_f32_16x16x32_bf16 v[82:85], v[172:175], v[196:199], v[82:85]
	v_mfma_f32_16x16x32_bf16 v[74:77], v[164:167], v[204:207], v[74:77]
	v_mfma_f32_16x16x32_bf16 v[66:69], v[172:175], v[204:207], v[66:69]
	s_setprio 0
	s_barrier
	s_add_i32 s91, s91, s37
	s_mov_b32 m0, s91
	ds_read_b128 v[176:179], v143 offset:16384
	ds_read_b128 v[180:183], v143 offset:17408
	ds_read_b128 v[184:187], v143 offset:18432
	ds_read_b128 v[188:191], v143 offset:19456
	ds_read_b128 v[192:195], v143 offset:20480
	ds_read_b128 v[196:199], v143 offset:21504
	ds_read_b128 v[200:203], v143 offset:22528
	ds_read_b128 v[204:207], v143 offset:23552
	global_load_lds_dwordx4 v16, s[28:29]
	s_add_i32 m0, s91, 0x2000
	s_add_u32 s92, s28, 0x80000
	s_addc_u32 s93, s29, 0
	s_add_i32 s91, s94, s37
	global_load_lds_dwordx4 v130, s[28:29]
	s_mov_b32 m0, s91
	v_lshl_add_u64 v[228:229], s[48:49], 0, v[132:133]
	global_load_lds_dwordx4 v16, s[92:93]
	s_add_i32 m0, s91, 0x2000
	s_nop 0
	global_load_lds_dwordx4 v130, s[92:93]
	v_lshl_add_u64 v[226:227], s[48:49], 0, v[134:135]
	s_mov_b32 m0, s45
	s_nop 0
	global_load_lds_dwordx4 v[226:227], off
	s_mov_b32 m0, s53
	s_nop 0
	global_load_lds_dwordx4 v[228:229], off
	s_waitcnt vmcnt(8)
	s_waitcnt lgkmcnt(0)
	s_barrier
	s_setprio 1
	s_waitcnt lgkmcnt(0)
	v_mfma_f32_16x16x32_bf16 v[62:65], v[144:147], v[176:179], 0
	v_mfma_f32_16x16x32_bf16 v[54:57], v[152:155], v[176:179], 0
	v_mfma_f32_16x16x32_bf16 v[46:49], v[144:147], v[184:187], 0
	v_mfma_f32_16x16x32_bf16 v[38:41], v[152:155], v[184:187], 0
	v_mfma_f32_16x16x32_bf16 v[30:33], v[144:147], v[192:195], 0
	v_mfma_f32_16x16x32_bf16 v[22:25], v[152:155], v[192:195], 0
	v_mfma_f32_16x16x32_bf16 v[12:15], v[144:147], v[200:203], 0
	v_mfma_f32_16x16x32_bf16 v[4:7], v[152:155], v[200:203], 0
	v_mfma_f32_16x16x32_bf16 v[62:65], v[148:151], v[180:183], v[62:65]
	v_mfma_f32_16x16x32_bf16 v[54:57], v[156:159], v[180:183], v[54:57]
	v_mfma_f32_16x16x32_bf16 v[46:49], v[148:151], v[188:191], v[46:49]
	v_mfma_f32_16x16x32_bf16 v[38:41], v[156:159], v[188:191], v[38:41]
	v_mfma_f32_16x16x32_bf16 v[30:33], v[148:151], v[196:199], v[30:33]
	v_mfma_f32_16x16x32_bf16 v[22:25], v[156:159], v[196:199], v[22:25]
	v_mfma_f32_16x16x32_bf16 v[12:15], v[148:151], v[204:207], v[12:15]
	v_mfma_f32_16x16x32_bf16 v[4:7], v[156:159], v[204:207], v[4:7]
	s_setprio 0
	s_setprio 1
	v_mfma_f32_16x16x32_bf16 v[58:61], v[160:163], v[176:179], 0
	v_mfma_f32_16x16x32_bf16 v[50:53], v[168:171], v[176:179], 0
	v_mfma_f32_16x16x32_bf16 v[42:45], v[160:163], v[184:187], 0
	v_mfma_f32_16x16x32_bf16 v[34:37], v[168:171], v[184:187], 0
	v_mfma_f32_16x16x32_bf16 v[26:29], v[160:163], v[192:195], 0
	v_mfma_f32_16x16x32_bf16 v[18:21], v[168:171], v[192:195], 0
	v_mfma_f32_16x16x32_bf16 v[8:11], v[160:163], v[200:203], 0
	v_mfma_f32_16x16x32_bf16 v[0:3], v[168:171], v[200:203], 0
	v_mfma_f32_16x16x32_bf16 v[58:61], v[164:167], v[180:183], v[58:61]
	v_mfma_f32_16x16x32_bf16 v[50:53], v[172:175], v[180:183], v[50:53]
	v_mfma_f32_16x16x32_bf16 v[42:45], v[164:167], v[188:191], v[42:45]
	v_mfma_f32_16x16x32_bf16 v[34:37], v[172:175], v[188:191], v[34:37]
	v_mfma_f32_16x16x32_bf16 v[26:29], v[164:167], v[196:199], v[26:29]
	v_mfma_f32_16x16x32_bf16 v[18:21], v[172:175], v[196:199], v[18:21]
	v_mfma_f32_16x16x32_bf16 v[8:11], v[164:167], v[204:207], v[8:11]
	v_mfma_f32_16x16x32_bf16 v[0:3], v[172:175], v[204:207], v[0:3]
	s_setprio 0
	s_barrier
	s_add_i32 s91, 0, 0x18000
	s_add_i32 s92, 0, 0x1c000
	v_add_u32_e32 v156, s91, v141
	v_add_u32_e32 v172, s92, v141
	ds_read_b128 v[144:147], v156
	ds_read_b128 v[148:151], v156 offset:1024
	ds_read_b128 v[152:155], v156 offset:2048
	ds_read_b128 v[156:159], v156 offset:3072
	ds_read_b128 v[160:163], v172
	ds_read_b128 v[164:167], v172 offset:1024
	ds_read_b128 v[168:171], v172 offset:2048
	ds_read_b128 v[172:175], v172 offset:3072
	s_add_u32 s48, s48, 0x80000
	s_addc_u32 s49, s49, 0
	s_mov_b32 m0, s57
	ds_read_b128 v[176:179], v143 offset:32768
	ds_read_b128 v[180:183], v143 offset:33792
	ds_read_b128 v[184:187], v143 offset:34816
	ds_read_b128 v[188:191], v143 offset:35840
	ds_read_b128 v[192:195], v143 offset:36864
	ds_read_b128 v[196:199], v143 offset:37888
	ds_read_b128 v[200:203], v143 offset:38912
	ds_read_b128 v[204:207], v143 offset:39936
	global_load_lds_dwordx4 v134, s[48:49]
	s_mov_b32 m0, s58
	s_nop 0
	global_load_lds_dwordx4 v132, s[48:49]
	s_waitcnt vmcnt(8)
	s_waitcnt lgkmcnt(0)
	s_barrier
	s_setprio 1
	s_waitcnt lgkmcnt(0)
	v_mfma_f32_16x16x32_bf16 v[126:129], v[144:147], v[176:179], v[126:129]
	v_mfma_f32_16x16x32_bf16 v[118:121], v[152:155], v[176:179], v[118:121]
	v_mfma_f32_16x16x32_bf16 v[110:113], v[144:147], v[184:187], v[110:113]
	v_mfma_f32_16x16x32_bf16 v[102:105], v[152:155], v[184:187], v[102:105]
	v_mfma_f32_16x16x32_bf16 v[94:97], v[144:147], v[192:195], v[94:97]
	v_mfma_f32_16x16x32_bf16 v[86:89], v[152:155], v[192:195], v[86:89]
	v_mfma_f32_16x16x32_bf16 v[78:81], v[144:147], v[200:203], v[78:81]
	v_mfma_f32_16x16x32_bf16 v[70:73], v[152:155], v[200:203], v[70:73]
	v_mfma_f32_16x16x32_bf16 v[126:129], v[148:151], v[180:183], v[126:129]
	v_mfma_f32_16x16x32_bf16 v[118:121], v[156:159], v[180:183], v[118:121]
	v_mfma_f32_16x16x32_bf16 v[110:113], v[148:151], v[188:191], v[110:113]
	v_mfma_f32_16x16x32_bf16 v[102:105], v[156:159], v[188:191], v[102:105]
	v_mfma_f32_16x16x32_bf16 v[94:97], v[148:151], v[196:199], v[94:97]
	v_mfma_f32_16x16x32_bf16 v[86:89], v[156:159], v[196:199], v[86:89]
	v_mfma_f32_16x16x32_bf16 v[78:81], v[148:151], v[204:207], v[78:81]
	v_mfma_f32_16x16x32_bf16 v[70:73], v[156:159], v[204:207], v[70:73]
	s_setprio 0
	s_setprio 1
	v_mfma_f32_16x16x32_bf16 v[122:125], v[160:163], v[176:179], v[122:125]
	v_mfma_f32_16x16x32_bf16 v[114:117], v[168:171], v[176:179], v[114:117]
	v_mfma_f32_16x16x32_bf16 v[106:109], v[160:163], v[184:187], v[106:109]
	v_mfma_f32_16x16x32_bf16 v[98:101], v[168:171], v[184:187], v[98:101]
	v_mfma_f32_16x16x32_bf16 v[90:93], v[160:163], v[192:195], v[90:93]
	v_mfma_f32_16x16x32_bf16 v[82:85], v[168:171], v[192:195], v[82:85]
	v_mfma_f32_16x16x32_bf16 v[74:77], v[160:163], v[200:203], v[74:77]
	v_mfma_f32_16x16x32_bf16 v[66:69], v[168:171], v[200:203], v[66:69]
	v_mfma_f32_16x16x32_bf16 v[122:125], v[164:167], v[180:183], v[122:125]
	v_mfma_f32_16x16x32_bf16 v[114:117], v[172:175], v[180:183], v[114:117]
	v_mfma_f32_16x16x32_bf16 v[106:109], v[164:167], v[188:191], v[106:109]
	v_mfma_f32_16x16x32_bf16 v[98:101], v[172:175], v[188:191], v[98:101]
	v_mfma_f32_16x16x32_bf16 v[90:93], v[164:167], v[196:199], v[90:93]
	v_mfma_f32_16x16x32_bf16 v[82:85], v[172:175], v[196:199], v[82:85]
	v_mfma_f32_16x16x32_bf16 v[74:77], v[164:167], v[204:207], v[74:77]
	v_mfma_f32_16x16x32_bf16 v[66:69], v[172:175], v[204:207], v[66:69]
	s_setprio 0
	s_barrier
	s_add_i32 s48, s91, s37
	s_add_u32 s28, s28, 0x80
	s_addc_u32 s29, s29, 0
	s_mov_b32 m0, s48
	ds_read_b128 v[176:179], v143 offset:49152
	ds_read_b128 v[180:183], v143 offset:50176
	ds_read_b128 v[184:187], v143 offset:51200
	ds_read_b128 v[188:191], v143 offset:52224
	ds_read_b128 v[192:195], v143 offset:53248
	ds_read_b128 v[196:199], v143 offset:54272
	ds_read_b128 v[200:203], v143 offset:55296
	ds_read_b128 v[204:207], v143 offset:56320
	global_load_lds_dwordx4 v16, s[28:29]
	s_add_i32 m0, s48, 0x2000
	s_add_i32 s48, s92, s37
	global_load_lds_dwordx4 v130, s[28:29]
	s_add_u32 s28, s28, 0x80000
	s_addc_u32 s29, s29, 0
	s_mov_b32 m0, s48
	s_nop 0
	global_load_lds_dwordx4 v16, s[28:29]
	s_add_i32 m0, s48, 0x2000
	s_nop 0
	global_load_lds_dwordx4 v130, s[28:29]
	v_lshl_add_u64 v[216:217], v[226:227], 0, s[34:35]
	s_mov_b32 m0, s59
	s_nop 0
	global_load_lds_dwordx4 v[216:217], off
	v_lshl_add_u64 v[216:217], v[228:229], 0, s[34:35]
	s_mov_b32 m0, s83
	s_nop 0
	global_load_lds_dwordx4 v[216:217], off
	s_waitcnt vmcnt(8)
	s_waitcnt lgkmcnt(0)
	s_barrier
	s_setprio 1
	s_waitcnt lgkmcnt(0)
	v_mfma_f32_16x16x32_bf16 v[62:65], v[144:147], v[176:179], v[62:65]
	v_mfma_f32_16x16x32_bf16 v[54:57], v[152:155], v[176:179], v[54:57]
	v_mfma_f32_16x16x32_bf16 v[46:49], v[144:147], v[184:187], v[46:49]
	v_mfma_f32_16x16x32_bf16 v[38:41], v[152:155], v[184:187], v[38:41]
	v_mfma_f32_16x16x32_bf16 v[30:33], v[144:147], v[192:195], v[30:33]
	v_mfma_f32_16x16x32_bf16 v[22:25], v[152:155], v[192:195], v[22:25]
	v_mfma_f32_16x16x32_bf16 v[12:15], v[144:147], v[200:203], v[12:15]
	v_mfma_f32_16x16x32_bf16 v[4:7], v[152:155], v[200:203], v[4:7]
	v_mfma_f32_16x16x32_bf16 v[62:65], v[148:151], v[180:183], v[62:65]
	v_mfma_f32_16x16x32_bf16 v[54:57], v[156:159], v[180:183], v[54:57]
	v_mfma_f32_16x16x32_bf16 v[46:49], v[148:151], v[188:191], v[46:49]
	v_mfma_f32_16x16x32_bf16 v[38:41], v[156:159], v[188:191], v[38:41]
	v_mfma_f32_16x16x32_bf16 v[30:33], v[148:151], v[196:199], v[30:33]
	v_mfma_f32_16x16x32_bf16 v[22:25], v[156:159], v[196:199], v[22:25]
	v_mfma_f32_16x16x32_bf16 v[12:15], v[148:151], v[204:207], v[12:15]
	v_mfma_f32_16x16x32_bf16 v[4:7], v[156:159], v[204:207], v[4:7]
	s_setprio 0
	s_setprio 1
	v_mfma_f32_16x16x32_bf16 v[58:61], v[160:163], v[176:179], v[58:61]
	v_mfma_f32_16x16x32_bf16 v[50:53], v[168:171], v[176:179], v[50:53]
	v_mfma_f32_16x16x32_bf16 v[42:45], v[160:163], v[184:187], v[42:45]
	v_mfma_f32_16x16x32_bf16 v[34:37], v[168:171], v[184:187], v[34:37]
	v_mfma_f32_16x16x32_bf16 v[26:29], v[160:163], v[192:195], v[26:29]
	v_mfma_f32_16x16x32_bf16 v[18:21], v[168:171], v[192:195], v[18:21]
	v_mfma_f32_16x16x32_bf16 v[8:11], v[160:163], v[200:203], v[8:11]
	v_mfma_f32_16x16x32_bf16 v[0:3], v[168:171], v[200:203], v[0:3]
	v_mfma_f32_16x16x32_bf16 v[58:61], v[164:167], v[180:183], v[58:61]
	v_mfma_f32_16x16x32_bf16 v[50:53], v[172:175], v[180:183], v[50:53]
	v_mfma_f32_16x16x32_bf16 v[42:45], v[164:167], v[188:191], v[42:45]
	v_mfma_f32_16x16x32_bf16 v[34:37], v[172:175], v[188:191], v[34:37]
	v_mfma_f32_16x16x32_bf16 v[26:29], v[164:167], v[196:199], v[26:29]
	v_mfma_f32_16x16x32_bf16 v[18:21], v[172:175], v[196:199], v[18:21]
	v_mfma_f32_16x16x32_bf16 v[8:11], v[164:167], v[204:207], v[8:11]
	v_mfma_f32_16x16x32_bf16 v[0:3], v[172:175], v[204:207], v[0:3]
	s_setprio 0
	s_barrier
	s_add_i32 s90, s90, 2
	s_add_u32 s46, s46, 0x100
	s_addc_u32 s47, s47, 0
	s_add_u32 s88, s88, 0x100
	s_addc_u32 s89, s89, 0
	s_cmp_gt_u32 s90, 29
	s_cbranch_scc1 .Lpz_I_exit
.LBB0_920:
	s_add_u32 s28, s46, 0xfff80080
	s_addc_u32 s29, s47, -1
	s_add_i32 s91, 0, 0x10000
	s_cmp_eq_u32 s90, 28
	s_cselect_b32 s49, s27, s29
	s_cselect_b32 s48, s86, s28
	s_cselect_b32 s29, s23, s89
	s_cselect_b32 s28, s87, s88
	s_add_i32 s94, 0, 0x14000
	v_add_u32_e32 v156, s91, v141
	v_add_u32_e32 v172, s94, v141
	ds_read_b128 v[144:147], v156
	ds_read_b128 v[148:151], v156 offset:1024
	ds_read_b128 v[152:155], v156 offset:2048
	ds_read_b128 v[156:159], v156 offset:3072
	ds_read_b128 v[160:163], v172
	ds_read_b128 v[164:167], v172 offset:1024
	ds_read_b128 v[168:171], v172 offset:2048
	ds_read_b128 v[172:175], v172 offset:3072
	s_add_i32 m0, s45, 0xc000
	ds_read_b128 v[176:179], v143
	ds_read_b128 v[180:183], v143 offset:1024
	ds_read_b128 v[184:187], v143 offset:2048
	ds_read_b128 v[188:191], v143 offset:3072
	ds_read_b128 v[192:195], v143 offset:4096
	ds_read_b128 v[196:199], v143 offset:5120
	ds_read_b128 v[200:203], v143 offset:6144
	ds_read_b128 v[204:207], v143 offset:7168
	global_load_lds_dwordx4 v136, s[46:47]
	s_add_i32 m0, s45, 0xe000
	s_nop 0
	global_load_lds_dwordx4 v138, s[46:47]
	s_waitcnt vmcnt(8)
	s_waitcnt lgkmcnt(0)
	s_barrier
	s_setprio 1
	s_waitcnt lgkmcnt(0)
	v_mfma_f32_16x16x32_bf16 v[126:129], v[144:147], v[176:179], v[126:129]
	v_mfma_f32_16x16x32_bf16 v[118:121], v[152:155], v[176:179], v[118:121]
	v_mfma_f32_16x16x32_bf16 v[110:113], v[144:147], v[184:187], v[110:113]
	v_mfma_f32_16x16x32_bf16 v[102:105], v[152:155], v[184:187], v[102:105]
	v_mfma_f32_16x16x32_bf16 v[94:97], v[144:147], v[192:195], v[94:97]
	v_mfma_f32_16x16x32_bf16 v[86:89], v[152:155], v[192:195], v[86:89]
	v_mfma_f32_16x16x32_bf16 v[78:81], v[144:147], v[200:203], v[78:81]
	v_mfma_f32_16x16x32_bf16 v[70:73], v[152:155], v[200:203], v[70:73]
	v_mfma_f32_16x16x32_bf16 v[126:129], v[148:151], v[180:183], v[126:129]
	v_mfma_f32_16x16x32_bf16 v[118:121], v[156:159], v[180:183], v[118:121]
	v_mfma_f32_16x16x32_bf16 v[110:113], v[148:151], v[188:191], v[110:113]
	v_mfma_f32_16x16x32_bf16 v[102:105], v[156:159], v[188:191], v[102:105]
	v_mfma_f32_16x16x32_bf16 v[94:97], v[148:151], v[196:199], v[94:97]
	v_mfma_f32_16x16x32_bf16 v[86:89], v[156:159], v[196:199], v[86:89]
	v_mfma_f32_16x16x32_bf16 v[78:81], v[148:151], v[204:207], v[78:81]
	v_mfma_f32_16x16x32_bf16 v[70:73], v[156:159], v[204:207], v[70:73]
	s_setprio 0
	s_setprio 1
	v_mfma_f32_16x16x32_bf16 v[122:125], v[160:163], v[176:179], v[122:125]
	v_mfma_f32_16x16x32_bf16 v[114:117], v[168:171], v[176:179], v[114:117]
	v_mfma_f32_16x16x32_bf16 v[106:109], v[160:163], v[184:187], v[106:109]
	v_mfma_f32_16x16x32_bf16 v[98:101], v[168:171], v[184:187], v[98:101]
	v_mfma_f32_16x16x32_bf16 v[90:93], v[160:163], v[192:195], v[90:93]
	v_mfma_f32_16x16x32_bf16 v[82:85], v[168:171], v[192:195], v[82:85]
	v_mfma_f32_16x16x32_bf16 v[74:77], v[160:163], v[200:203], v[74:77]
	v_mfma_f32_16x16x32_bf16 v[66:69], v[168:171], v[200:203], v[66:69]
	v_mfma_f32_16x16x32_bf16 v[122:125], v[164:167], v[180:183], v[122:125]
	v_mfma_f32_16x16x32_bf16 v[114:117], v[172:175], v[180:183], v[114:117]
	v_mfma_f32_16x16x32_bf16 v[106:109], v[164:167], v[188:191], v[106:109]
	v_mfma_f32_16x16x32_bf16 v[98:101], v[172:175], v[188:191], v[98:101]
	v_mfma_f32_16x16x32_bf16 v[90:93], v[164:167], v[196:199], v[90:93]
	v_mfma_f32_16x16x32_bf16 v[82:85], v[172:175], v[196:199], v[82:85]
	v_mfma_f32_16x16x32_bf16 v[74:77], v[164:167], v[204:207], v[74:77]
	v_mfma_f32_16x16x32_bf16 v[66:69], v[172:175], v[204:207], v[66:69]
	s_setprio 0
	s_barrier
	s_add_i32 s91, s91, s37
	s_mov_b32 m0, s91
	ds_read_b128 v[176:179], v143 offset:16384
	ds_read_b128 v[180:183], v143 offset:17408
	ds_read_b128 v[184:187], v143 offset:18432
	ds_read_b128 v[188:191], v143 offset:19456
	ds_read_b128 v[192:195], v143 offset:20480
	ds_read_b128 v[196:199], v143 offset:21504
	ds_read_b128 v[200:203], v143 offset:22528
	ds_read_b128 v[204:207], v143 offset:23552
	global_load_lds_dwordx4 v16, s[28:29]
	s_add_i32 m0, s91, 0x2000
	s_add_u32 s92, s28, 0x80000
	s_addc_u32 s93, s29, 0
	s_add_i32 s91, s94, s37
	global_load_lds_dwordx4 v130, s[28:29]
	s_mov_b32 m0, s91
	v_lshl_add_u64 v[228:229], s[48:49], 0, v[132:133]
	global_load_lds_dwordx4 v16, s[92:93]
	s_add_i32 m0, s91, 0x2000
	s_nop 0
	global_load_lds_dwordx4 v130, s[92:93]
	v_lshl_add_u64 v[226:227], s[48:49], 0, v[134:135]
	s_mov_b32 m0, s45
	s_nop 0
	global_load_lds_dwordx4 v[226:227], off
	s_mov_b32 m0, s53
	s_nop 0
	global_load_lds_dwordx4 v[228:229], off
	s_waitcnt vmcnt(8)
	s_waitcnt lgkmcnt(0)
	s_barrier
	s_setprio 1
	s_waitcnt lgkmcnt(0)
	v_mfma_f32_16x16x32_bf16 v[62:65], v[144:147], v[176:179], v[62:65]
	v_mfma_f32_16x16x32_bf16 v[54:57], v[152:155], v[176:179], v[54:57]
	v_mfma_f32_16x16x32_bf16 v[46:49], v[144:147], v[184:187], v[46:49]
	v_mfma_f32_16x16x32_bf16 v[38:41], v[152:155], v[184:187], v[38:41]
	v_mfma_f32_16x16x32_bf16 v[30:33], v[144:147], v[192:195], v[30:33]
	v_mfma_f32_16x16x32_bf16 v[22:25], v[152:155], v[192:195], v[22:25]
	v_mfma_f32_16x16x32_bf16 v[12:15], v[144:147], v[200:203], v[12:15]
	v_mfma_f32_16x16x32_bf16 v[4:7], v[152:155], v[200:203], v[4:7]
	v_mfma_f32_16x16x32_bf16 v[62:65], v[148:151], v[180:183], v[62:65]
	v_mfma_f32_16x16x32_bf16 v[54:57], v[156:159], v[180:183], v[54:57]
	v_mfma_f32_16x16x32_bf16 v[46:49], v[148:151], v[188:191], v[46:49]
	v_mfma_f32_16x16x32_bf16 v[38:41], v[156:159], v[188:191], v[38:41]
	v_mfma_f32_16x16x32_bf16 v[30:33], v[148:151], v[196:199], v[30:33]
	v_mfma_f32_16x16x32_bf16 v[22:25], v[156:159], v[196:199], v[22:25]
	v_mfma_f32_16x16x32_bf16 v[12:15], v[148:151], v[204:207], v[12:15]
	v_mfma_f32_16x16x32_bf16 v[4:7], v[156:159], v[204:207], v[4:7]
	s_setprio 0
	s_setprio 1
	v_mfma_f32_16x16x32_bf16 v[58:61], v[160:163], v[176:179], v[58:61]
	v_mfma_f32_16x16x32_bf16 v[50:53], v[168:171], v[176:179], v[50:53]
	v_mfma_f32_16x16x32_bf16 v[42:45], v[160:163], v[184:187], v[42:45]
	v_mfma_f32_16x16x32_bf16 v[34:37], v[168:171], v[184:187], v[34:37]
	v_mfma_f32_16x16x32_bf16 v[26:29], v[160:163], v[192:195], v[26:29]
	v_mfma_f32_16x16x32_bf16 v[18:21], v[168:171], v[192:195], v[18:21]
	v_mfma_f32_16x16x32_bf16 v[8:11], v[160:163], v[200:203], v[8:11]
	v_mfma_f32_16x16x32_bf16 v[0:3], v[168:171], v[200:203], v[0:3]
	v_mfma_f32_16x16x32_bf16 v[58:61], v[164:167], v[180:183], v[58:61]
	v_mfma_f32_16x16x32_bf16 v[50:53], v[172:175], v[180:183], v[50:53]
	v_mfma_f32_16x16x32_bf16 v[42:45], v[164:167], v[188:191], v[42:45]
	v_mfma_f32_16x16x32_bf16 v[34:37], v[172:175], v[188:191], v[34:37]
	v_mfma_f32_16x16x32_bf16 v[26:29], v[164:167], v[196:199], v[26:29]
	v_mfma_f32_16x16x32_bf16 v[18:21], v[172:175], v[196:199], v[18:21]
	v_mfma_f32_16x16x32_bf16 v[8:11], v[164:167], v[204:207], v[8:11]
	v_mfma_f32_16x16x32_bf16 v[0:3], v[172:175], v[204:207], v[0:3]
	s_setprio 0
	s_barrier
	s_add_i32 s91, 0, 0x18000
	s_add_i32 s92, 0, 0x1c000
	v_add_u32_e32 v156, s91, v141
	v_add_u32_e32 v172, s92, v141
	ds_read_b128 v[144:147], v156
	ds_read_b128 v[148:151], v156 offset:1024
	ds_read_b128 v[152:155], v156 offset:2048
	ds_read_b128 v[156:159], v156 offset:3072
	ds_read_b128 v[160:163], v172
	ds_read_b128 v[164:167], v172 offset:1024
	ds_read_b128 v[168:171], v172 offset:2048
	ds_read_b128 v[172:175], v172 offset:3072
	s_add_u32 s48, s48, 0x80000
	s_addc_u32 s49, s49, 0
	s_mov_b32 m0, s57
	ds_read_b128 v[176:179], v143 offset:32768
	ds_read_b128 v[180:183], v143 offset:33792
	ds_read_b128 v[184:187], v143 offset:34816
	ds_read_b128 v[188:191], v143 offset:35840
	ds_read_b128 v[192:195], v143 offset:36864
	ds_read_b128 v[196:199], v143 offset:37888
	ds_read_b128 v[200:203], v143 offset:38912
	ds_read_b128 v[204:207], v143 offset:39936
	global_load_lds_dwordx4 v134, s[48:49]
	s_mov_b32 m0, s58
	s_nop 0
	global_load_lds_dwordx4 v132, s[48:49]
	s_waitcnt vmcnt(8)
	s_waitcnt lgkmcnt(0)
	s_barrier
	s_setprio 1
	s_waitcnt lgkmcnt(0)
	v_mfma_f32_16x16x32_bf16 v[126:129], v[144:147], v[176:179], v[126:129]
	v_mfma_f32_16x16x32_bf16 v[118:121], v[152:155], v[176:179], v[118:121]
	v_mfma_f32_16x16x32_bf16 v[110:113], v[144:147], v[184:187], v[110:113]
	v_mfma_f32_16x16x32_bf16 v[102:105], v[152:155], v[184:187], v[102:105]
	v_mfma_f32_16x16x32_bf16 v[94:97], v[144:147], v[192:195], v[94:97]
	v_mfma_f32_16x16x32_bf16 v[86:89], v[152:155], v[192:195], v[86:89]
	v_mfma_f32_16x16x32_bf16 v[78:81], v[144:147], v[200:203], v[78:81]
	v_mfma_f32_16x16x32_bf16 v[70:73], v[152:155], v[200:203], v[70:73]
	v_mfma_f32_16x16x32_bf16 v[126:129], v[148:151], v[180:183], v[126:129]
	v_mfma_f32_16x16x32_bf16 v[118:121], v[156:159], v[180:183], v[118:121]
	v_mfma_f32_16x16x32_bf16 v[110:113], v[148:151], v[188:191], v[110:113]
	v_mfma_f32_16x16x32_bf16 v[102:105], v[156:159], v[188:191], v[102:105]
	v_mfma_f32_16x16x32_bf16 v[94:97], v[148:151], v[196:199], v[94:97]
	v_mfma_f32_16x16x32_bf16 v[86:89], v[156:159], v[196:199], v[86:89]
	v_mfma_f32_16x16x32_bf16 v[78:81], v[148:151], v[204:207], v[78:81]
	v_mfma_f32_16x16x32_bf16 v[70:73], v[156:159], v[204:207], v[70:73]
	s_setprio 0
	s_setprio 1
	v_mfma_f32_16x16x32_bf16 v[122:125], v[160:163], v[176:179], v[122:125]
	v_mfma_f32_16x16x32_bf16 v[114:117], v[168:171], v[176:179], v[114:117]
	v_mfma_f32_16x16x32_bf16 v[106:109], v[160:163], v[184:187], v[106:109]
	v_mfma_f32_16x16x32_bf16 v[98:101], v[168:171], v[184:187], v[98:101]
	v_mfma_f32_16x16x32_bf16 v[90:93], v[160:163], v[192:195], v[90:93]
	v_mfma_f32_16x16x32_bf16 v[82:85], v[168:171], v[192:195], v[82:85]
	v_mfma_f32_16x16x32_bf16 v[74:77], v[160:163], v[200:203], v[74:77]
	v_mfma_f32_16x16x32_bf16 v[66:69], v[168:171], v[200:203], v[66:69]
	v_mfma_f32_16x16x32_bf16 v[122:125], v[164:167], v[180:183], v[122:125]
	v_mfma_f32_16x16x32_bf16 v[114:117], v[172:175], v[180:183], v[114:117]
	v_mfma_f32_16x16x32_bf16 v[106:109], v[164:167], v[188:191], v[106:109]
	v_mfma_f32_16x16x32_bf16 v[98:101], v[172:175], v[188:191], v[98:101]
	v_mfma_f32_16x16x32_bf16 v[90:93], v[164:167], v[196:199], v[90:93]
	v_mfma_f32_16x16x32_bf16 v[82:85], v[172:175], v[196:199], v[82:85]
	v_mfma_f32_16x16x32_bf16 v[74:77], v[164:167], v[204:207], v[74:77]
	v_mfma_f32_16x16x32_bf16 v[66:69], v[172:175], v[204:207], v[66:69]
	s_setprio 0
	s_barrier
	s_add_i32 s48, s91, s37
	s_add_u32 s28, s28, 0x80
	s_addc_u32 s29, s29, 0
	s_mov_b32 m0, s48
	ds_read_b128 v[176:179], v143 offset:49152
	ds_read_b128 v[180:183], v143 offset:50176
	ds_read_b128 v[184:187], v143 offset:51200
	ds_read_b128 v[188:191], v143 offset:52224
	ds_read_b128 v[192:195], v143 offset:53248
	ds_read_b128 v[196:199], v143 offset:54272
	ds_read_b128 v[200:203], v143 offset:55296
	ds_read_b128 v[204:207], v143 offset:56320
	global_load_lds_dwordx4 v16, s[28:29]
	s_add_i32 m0, s48, 0x2000
	s_add_i32 s48, s92, s37
	global_load_lds_dwordx4 v130, s[28:29]
	s_add_u32 s28, s28, 0x80000
	s_addc_u32 s29, s29, 0
	s_mov_b32 m0, s48
	s_nop 0
	global_load_lds_dwordx4 v16, s[28:29]
	s_add_i32 m0, s48, 0x2000
	s_nop 0
	global_load_lds_dwordx4 v130, s[28:29]
	v_lshl_add_u64 v[216:217], v[226:227], 0, s[34:35]
	s_mov_b32 m0, s59
	s_nop 0
	global_load_lds_dwordx4 v[216:217], off
	v_lshl_add_u64 v[216:217], v[228:229], 0, s[34:35]
	s_mov_b32 m0, s83
	s_nop 0
	global_load_lds_dwordx4 v[216:217], off
	s_waitcnt vmcnt(8)
	s_waitcnt lgkmcnt(0)
	s_barrier
	s_setprio 1
	s_waitcnt lgkmcnt(0)
	v_mfma_f32_16x16x32_bf16 v[62:65], v[144:147], v[176:179], v[62:65]
	v_mfma_f32_16x16x32_bf16 v[54:57], v[152:155], v[176:179], v[54:57]
	v_mfma_f32_16x16x32_bf16 v[46:49], v[144:147], v[184:187], v[46:49]
	v_mfma_f32_16x16x32_bf16 v[38:41], v[152:155], v[184:187], v[38:41]
	v_mfma_f32_16x16x32_bf16 v[30:33], v[144:147], v[192:195], v[30:33]
	v_mfma_f32_16x16x32_bf16 v[22:25], v[152:155], v[192:195], v[22:25]
	v_mfma_f32_16x16x32_bf16 v[12:15], v[144:147], v[200:203], v[12:15]
	v_mfma_f32_16x16x32_bf16 v[4:7], v[152:155], v[200:203], v[4:7]
	v_mfma_f32_16x16x32_bf16 v[62:65], v[148:151], v[180:183], v[62:65]
	v_mfma_f32_16x16x32_bf16 v[54:57], v[156:159], v[180:183], v[54:57]
	v_mfma_f32_16x16x32_bf16 v[46:49], v[148:151], v[188:191], v[46:49]
	v_mfma_f32_16x16x32_bf16 v[38:41], v[156:159], v[188:191], v[38:41]
	v_mfma_f32_16x16x32_bf16 v[30:33], v[148:151], v[196:199], v[30:33]
	v_mfma_f32_16x16x32_bf16 v[22:25], v[156:159], v[196:199], v[22:25]
	v_mfma_f32_16x16x32_bf16 v[12:15], v[148:151], v[204:207], v[12:15]
	v_mfma_f32_16x16x32_bf16 v[4:7], v[156:159], v[204:207], v[4:7]
	s_setprio 0
	s_setprio 1
	v_mfma_f32_16x16x32_bf16 v[58:61], v[160:163], v[176:179], v[58:61]
	v_mfma_f32_16x16x32_bf16 v[50:53], v[168:171], v[176:179], v[50:53]
	v_mfma_f32_16x16x32_bf16 v[42:45], v[160:163], v[184:187], v[42:45]
	v_mfma_f32_16x16x32_bf16 v[34:37], v[168:171], v[184:187], v[34:37]
	v_mfma_f32_16x16x32_bf16 v[26:29], v[160:163], v[192:195], v[26:29]
	v_mfma_f32_16x16x32_bf16 v[18:21], v[168:171], v[192:195], v[18:21]
	v_mfma_f32_16x16x32_bf16 v[8:11], v[160:163], v[200:203], v[8:11]
	v_mfma_f32_16x16x32_bf16 v[0:3], v[168:171], v[200:203], v[0:3]
	v_mfma_f32_16x16x32_bf16 v[58:61], v[164:167], v[180:183], v[58:61]
	v_mfma_f32_16x16x32_bf16 v[50:53], v[172:175], v[180:183], v[50:53]
	v_mfma_f32_16x16x32_bf16 v[42:45], v[164:167], v[188:191], v[42:45]
	v_mfma_f32_16x16x32_bf16 v[34:37], v[172:175], v[188:191], v[34:37]
	v_mfma_f32_16x16x32_bf16 v[26:29], v[164:167], v[196:199], v[26:29]
	v_mfma_f32_16x16x32_bf16 v[18:21], v[172:175], v[196:199], v[18:21]
	v_mfma_f32_16x16x32_bf16 v[8:11], v[164:167], v[204:207], v[8:11]
	v_mfma_f32_16x16x32_bf16 v[0:3], v[172:175], v[204:207], v[0:3]
	s_setprio 0
	s_barrier
	s_add_i32 s90, s90, 2
	s_add_u32 s46, s46, 0x100
	s_addc_u32 s47, s47, 0
	s_add_u32 s88, s88, 0x100
	s_addc_u32 s89, s89, 0
	s_cmp_gt_u32 s90, 29
	s_cbranch_scc0 .LBB0_920

.LBB0_991:
	s_add_u32 s42, s42, 0x100
	s_addc_u32 s43, s43, 0
	s_mov_b32 s86, -2
	s_add_u32 s36, s26, 0x100
	s_addc_u32 s37, s27, 0
	s_add_i32 s87, 0, 0x10000
	s_cmpk_eq_i32 s86, 0x54
	s_cselect_b32 s41, s19, s37
	s_cselect_b32 s40, s18, s36
	s_cselect_b32 s29, s23, s43
	s_cselect_b32 s28, s22, s42
	s_add_i32 s88, 0, 0x14000
	v_add_u32_e32 v142, s87, v203
	v_add_u32_e32 v158, s88, v203
	ds_read_b128 v[130:133], v142
	ds_read_b128 v[134:137], v142 offset:1024
	ds_read_b128 v[138:141], v142 offset:2048
	ds_read_b128 v[142:145], v142 offset:3072
	ds_read_b128 v[146:149], v158
	ds_read_b128 v[150:153], v158 offset:1024
	ds_read_b128 v[154:157], v158 offset:2048
	ds_read_b128 v[158:161], v158 offset:3072
	s_add_i32 m0, s47, 0xc000
	ds_read_b128 v[162:165], v205
	ds_read_b128 v[166:169], v205 offset:1024
	ds_read_b128 v[170:173], v205 offset:2048
	ds_read_b128 v[174:177], v205 offset:3072
	ds_read_b128 v[178:181], v205 offset:4096
	ds_read_b128 v[192:195], v205 offset:5120
	ds_read_b128 v[196:199], v205 offset:6144
	ds_read_b128 v[224:227], v205 offset:7168
	global_load_lds_dwordx4 v188, s[26:27]
	s_add_i32 m0, s47, 0xe000
	s_nop 0
	global_load_lds_dwordx4 v190, s[26:27]
	s_waitcnt vmcnt(8)
	s_waitcnt lgkmcnt(0)
	s_barrier
	s_setprio 1
	s_waitcnt lgkmcnt(0)
	v_mfma_f32_16x16x32_bf16 v[126:129], v[130:133], v[162:165], 0
	v_mfma_f32_16x16x32_bf16 v[122:125], v[138:141], v[162:165], 0
	v_mfma_f32_16x16x32_bf16 v[114:117], v[130:133], v[170:173], 0
	v_mfma_f32_16x16x32_bf16 v[106:109], v[138:141], v[170:173], 0
	v_mfma_f32_16x16x32_bf16 v[98:101], v[130:133], v[178:181], 0
	v_mfma_f32_16x16x32_bf16 v[90:93], v[138:141], v[178:181], 0
	v_mfma_f32_16x16x32_bf16 v[82:85], v[130:133], v[196:199], 0
	v_mfma_f32_16x16x32_bf16 v[74:77], v[138:141], v[196:199], 0
	v_mfma_f32_16x16x32_bf16 v[126:129], v[134:137], v[166:169], v[126:129]
	v_mfma_f32_16x16x32_bf16 v[122:125], v[142:145], v[166:169], v[122:125]
	v_mfma_f32_16x16x32_bf16 v[114:117], v[134:137], v[174:177], v[114:117]
	v_mfma_f32_16x16x32_bf16 v[106:109], v[142:145], v[174:177], v[106:109]
	v_mfma_f32_16x16x32_bf16 v[98:101], v[134:137], v[192:195], v[98:101]
	v_mfma_f32_16x16x32_bf16 v[90:93], v[142:145], v[192:195], v[90:93]
	v_mfma_f32_16x16x32_bf16 v[82:85], v[134:137], v[224:227], v[82:85]
	v_mfma_f32_16x16x32_bf16 v[74:77], v[142:145], v[224:227], v[74:77]
	s_setprio 0
	s_setprio 1
	v_mfma_f32_16x16x32_bf16 v[118:121], v[146:149], v[162:165], 0
	v_mfma_f32_16x16x32_bf16 v[110:113], v[154:157], v[162:165], 0
	v_mfma_f32_16x16x32_bf16 v[102:105], v[146:149], v[170:173], 0
	v_mfma_f32_16x16x32_bf16 v[94:97], v[154:157], v[170:173], 0
	v_mfma_f32_16x16x32_bf16 v[86:89], v[146:149], v[178:181], 0
	v_mfma_f32_16x16x32_bf16 v[78:81], v[154:157], v[178:181], 0
	v_mfma_f32_16x16x32_bf16 v[70:73], v[146:149], v[196:199], 0
	v_mfma_f32_16x16x32_bf16 v[66:69], v[154:157], v[196:199], 0
	v_mfma_f32_16x16x32_bf16 v[118:121], v[150:153], v[166:169], v[118:121]
	v_mfma_f32_16x16x32_bf16 v[110:113], v[158:161], v[166:169], v[110:113]
	v_mfma_f32_16x16x32_bf16 v[102:105], v[150:153], v[174:177], v[102:105]
	v_mfma_f32_16x16x32_bf16 v[94:97], v[158:161], v[174:177], v[94:97]
	v_mfma_f32_16x16x32_bf16 v[86:89], v[150:153], v[192:195], v[86:89]
	v_mfma_f32_16x16x32_bf16 v[78:81], v[158:161], v[192:195], v[78:81]
	v_mfma_f32_16x16x32_bf16 v[70:73], v[150:153], v[224:227], v[70:73]
	v_mfma_f32_16x16x32_bf16 v[66:69], v[158:161], v[224:227], v[66:69]
	s_setprio 0
	s_barrier
	s_add_i32 s26, s87, s45
	v_lshl_add_u64 v[200:201], s[28:29], 0, v[16:17]
	s_mov_b32 m0, s26
	ds_read_b128 v[162:165], v205 offset:16384
	ds_read_b128 v[166:169], v205 offset:17408
	ds_read_b128 v[170:173], v205 offset:18432
	ds_read_b128 v[174:177], v205 offset:19456
	ds_read_b128 v[178:181], v205 offset:20480
	ds_read_b128 v[192:195], v205 offset:21504
	ds_read_b128 v[196:199], v205 offset:22528
	ds_read_b128 v[224:227], v205 offset:23552
	global_load_lds_dwordx4 v[200:201], off
	s_add_i32 m0, s26, 0x2000
	s_add_u32 s26, s28, 0x160000
	v_lshl_add_u64 v[206:207], s[28:29], 0, v[182:183]
	s_addc_u32 s27, s29, 0
	s_add_i32 s87, s88, s45
	global_load_lds_dwordx4 v[206:207], off
	s_mov_b32 m0, s87
	v_lshl_add_u64 v[228:229], s[40:41], 0, v[184:185]
	global_load_lds_dwordx4 v16, s[26:27]
	s_add_i32 m0, s87, 0x2000
	s_nop 0
	global_load_lds_dwordx4 v182, s[26:27]
	v_lshl_add_u64 v[216:217], s[40:41], 0, v[186:187]
	s_mov_b32 m0, s47
	s_nop 0
	global_load_lds_dwordx4 v[216:217], off
	s_mov_b32 m0, s48
	s_nop 0
	global_load_lds_dwordx4 v[228:229], off
	s_waitcnt vmcnt(8)
	s_waitcnt lgkmcnt(0)
	s_barrier
	s_setprio 1
	s_waitcnt lgkmcnt(0)
	v_mfma_f32_16x16x32_bf16 v[62:65], v[130:133], v[162:165], 0
	v_mfma_f32_16x16x32_bf16 v[58:61], v[138:141], v[162:165], 0
	v_mfma_f32_16x16x32_bf16 v[50:53], v[130:133], v[170:173], 0
	v_mfma_f32_16x16x32_bf16 v[42:45], v[138:141], v[170:173], 0
	v_mfma_f32_16x16x32_bf16 v[34:37], v[130:133], v[178:181], 0
	v_mfma_f32_16x16x32_bf16 v[26:29], v[138:141], v[178:181], 0
	v_mfma_f32_16x16x32_bf16 v[18:21], v[130:133], v[196:199], 0
	v_mfma_f32_16x16x32_bf16 v[8:11], v[138:141], v[196:199], 0
	v_mfma_f32_16x16x32_bf16 v[62:65], v[134:137], v[166:169], v[62:65]
	v_mfma_f32_16x16x32_bf16 v[58:61], v[142:145], v[166:169], v[58:61]
	v_mfma_f32_16x16x32_bf16 v[50:53], v[134:137], v[174:177], v[50:53]
	v_mfma_f32_16x16x32_bf16 v[42:45], v[142:145], v[174:177], v[42:45]
	v_mfma_f32_16x16x32_bf16 v[34:37], v[134:137], v[192:195], v[34:37]
	v_mfma_f32_16x16x32_bf16 v[26:29], v[142:145], v[192:195], v[26:29]
	v_mfma_f32_16x16x32_bf16 v[18:21], v[134:137], v[224:227], v[18:21]
	v_mfma_f32_16x16x32_bf16 v[8:11], v[142:145], v[224:227], v[8:11]
	s_setprio 0
	s_setprio 1
	v_mfma_f32_16x16x32_bf16 v[54:57], v[146:149], v[162:165], 0
	v_mfma_f32_16x16x32_bf16 v[46:49], v[154:157], v[162:165], 0
	v_mfma_f32_16x16x32_bf16 v[38:41], v[146:149], v[170:173], 0
	v_mfma_f32_16x16x32_bf16 v[30:33], v[154:157], v[170:173], 0
	v_mfma_f32_16x16x32_bf16 v[22:25], v[146:149], v[178:181], 0
	v_mfma_f32_16x16x32_bf16 v[12:15], v[154:157], v[178:181], 0
	v_mfma_f32_16x16x32_bf16 v[4:7], v[146:149], v[196:199], 0
	v_mfma_f32_16x16x32_bf16 v[0:3], v[154:157], v[196:199], 0
	v_mfma_f32_16x16x32_bf16 v[54:57], v[150:153], v[166:169], v[54:57]
	v_mfma_f32_16x16x32_bf16 v[46:49], v[158:161], v[166:169], v[46:49]
	v_mfma_f32_16x16x32_bf16 v[38:41], v[150:153], v[174:177], v[38:41]
	v_mfma_f32_16x16x32_bf16 v[30:33], v[158:161], v[174:177], v[30:33]
	v_mfma_f32_16x16x32_bf16 v[22:25], v[150:153], v[192:195], v[22:25]
	v_mfma_f32_16x16x32_bf16 v[12:15], v[158:161], v[192:195], v[12:15]
	v_mfma_f32_16x16x32_bf16 v[4:7], v[150:153], v[224:227], v[4:7]
	v_mfma_f32_16x16x32_bf16 v[0:3], v[158:161], v[224:227], v[0:3]
	s_setprio 0
	s_barrier
	s_add_i32 s87, 0, 0x18000
	s_add_i32 s88, 0, 0x1c000
	v_add_u32_e32 v142, s87, v203
	v_add_u32_e32 v158, s88, v203
	ds_read_b128 v[130:133], v142
	ds_read_b128 v[134:137], v142 offset:1024
	ds_read_b128 v[138:141], v142 offset:2048
	ds_read_b128 v[142:145], v142 offset:3072
	ds_read_b128 v[146:149], v158
	ds_read_b128 v[150:153], v158 offset:1024
	ds_read_b128 v[154:157], v158 offset:2048
	ds_read_b128 v[158:161], v158 offset:3072
	s_add_u32 s26, s40, 0x160000
	s_addc_u32 s27, s41, 0
	s_mov_b32 m0, s49
	ds_read_b128 v[162:165], v205 offset:32768
	ds_read_b128 v[166:169], v205 offset:33792
	ds_read_b128 v[170:173], v205 offset:34816
	ds_read_b128 v[174:177], v205 offset:35840
	ds_read_b128 v[178:181], v205 offset:36864
	ds_read_b128 v[192:195], v205 offset:37888
	ds_read_b128 v[196:199], v205 offset:38912
	ds_read_b128 v[224:227], v205 offset:39936
	global_load_lds_dwordx4 v186, s[26:27]
	s_mov_b32 m0, s50
	s_nop 0
	global_load_lds_dwordx4 v184, s[26:27]
	s_waitcnt vmcnt(8)
	s_waitcnt lgkmcnt(0)
	s_barrier
	s_setprio 1
	s_waitcnt lgkmcnt(0)
	v_mfma_f32_16x16x32_bf16 v[126:129], v[130:133], v[162:165], v[126:129]
	v_mfma_f32_16x16x32_bf16 v[122:125], v[138:141], v[162:165], v[122:125]
	v_mfma_f32_16x16x32_bf16 v[114:117], v[130:133], v[170:173], v[114:117]
	v_mfma_f32_16x16x32_bf16 v[106:109], v[138:141], v[170:173], v[106:109]
	v_mfma_f32_16x16x32_bf16 v[98:101], v[130:133], v[178:181], v[98:101]
	v_mfma_f32_16x16x32_bf16 v[90:93], v[138:141], v[178:181], v[90:93]
	v_mfma_f32_16x16x32_bf16 v[82:85], v[130:133], v[196:199], v[82:85]
	v_mfma_f32_16x16x32_bf16 v[74:77], v[138:141], v[196:199], v[74:77]
	v_mfma_f32_16x16x32_bf16 v[126:129], v[134:137], v[166:169], v[126:129]
	v_mfma_f32_16x16x32_bf16 v[122:125], v[142:145], v[166:169], v[122:125]
	v_mfma_f32_16x16x32_bf16 v[114:117], v[134:137], v[174:177], v[114:117]
	v_mfma_f32_16x16x32_bf16 v[106:109], v[142:145], v[174:177], v[106:109]
	v_mfma_f32_16x16x32_bf16 v[98:101], v[134:137], v[192:195], v[98:101]
	v_mfma_f32_16x16x32_bf16 v[90:93], v[142:145], v[192:195], v[90:93]
	v_mfma_f32_16x16x32_bf16 v[82:85], v[134:137], v[224:227], v[82:85]
	v_mfma_f32_16x16x32_bf16 v[74:77], v[142:145], v[224:227], v[74:77]
	s_setprio 0
	s_setprio 1
	v_mfma_f32_16x16x32_bf16 v[118:121], v[146:149], v[162:165], v[118:121]
	v_mfma_f32_16x16x32_bf16 v[110:113], v[154:157], v[162:165], v[110:113]
	v_mfma_f32_16x16x32_bf16 v[102:105], v[146:149], v[170:173], v[102:105]
	v_mfma_f32_16x16x32_bf16 v[94:97], v[154:157], v[170:173], v[94:97]
	v_mfma_f32_16x16x32_bf16 v[86:89], v[146:149], v[178:181], v[86:89]
	v_mfma_f32_16x16x32_bf16 v[78:81], v[154:157], v[178:181], v[78:81]
	v_mfma_f32_16x16x32_bf16 v[70:73], v[146:149], v[196:199], v[70:73]
	v_mfma_f32_16x16x32_bf16 v[66:69], v[154:157], v[196:199], v[66:69]
	v_mfma_f32_16x16x32_bf16 v[118:121], v[150:153], v[166:169], v[118:121]
	v_mfma_f32_16x16x32_bf16 v[110:113], v[158:161], v[166:169], v[110:113]
	v_mfma_f32_16x16x32_bf16 v[102:105], v[150:153], v[174:177], v[102:105]
	v_mfma_f32_16x16x32_bf16 v[94:97], v[158:161], v[174:177], v[94:97]
	v_mfma_f32_16x16x32_bf16 v[86:89], v[150:153], v[192:195], v[86:89]
	v_mfma_f32_16x16x32_bf16 v[78:81], v[158:161], v[192:195], v[78:81]
	v_mfma_f32_16x16x32_bf16 v[70:73], v[150:153], v[224:227], v[70:73]
	v_mfma_f32_16x16x32_bf16 v[66:69], v[158:161], v[224:227], v[66:69]
	s_setprio 0
	s_barrier
	s_add_i32 s26, s87, s45
	v_lshl_add_u64 v[200:201], v[200:201], 0, s[34:35]
	s_mov_b32 m0, s26
	ds_read_b128 v[162:165], v205 offset:49152
	ds_read_b128 v[166:169], v205 offset:50176
	ds_read_b128 v[170:173], v205 offset:51200
	ds_read_b128 v[174:177], v205 offset:52224
	ds_read_b128 v[178:181], v205 offset:53248
	ds_read_b128 v[192:195], v205 offset:54272
	ds_read_b128 v[196:199], v205 offset:55296
	ds_read_b128 v[224:227], v205 offset:56320
	global_load_lds_dwordx4 v[200:201], off
	s_add_i32 m0, s26, 0x2000
	s_add_u32 s26, s28, 0x160080
	v_lshl_add_u64 v[200:201], v[206:207], 0, s[34:35]
	s_addc_u32 s27, s29, 0
	s_add_i32 s28, s88, s45
	global_load_lds_dwordx4 v[200:201], off
	s_mov_b32 m0, s28
	s_nop 0
	global_load_lds_dwordx4 v16, s[26:27]
	s_add_i32 m0, s28, 0x2000
	s_nop 0
	global_load_lds_dwordx4 v182, s[26:27]
	v_lshl_add_u64 v[200:201], v[216:217], 0, s[34:35]
	s_mov_b32 m0, s53
	s_nop 0
	global_load_lds_dwordx4 v[200:201], off
	v_lshl_add_u64 v[200:201], v[228:229], 0, s[34:35]
	s_mov_b32 m0, s57
	s_nop 0
	global_load_lds_dwordx4 v[200:201], off
	s_waitcnt vmcnt(8)
	s_waitcnt lgkmcnt(0)
	s_barrier
	s_setprio 1
	s_waitcnt lgkmcnt(0)
	v_mfma_f32_16x16x32_bf16 v[62:65], v[130:133], v[162:165], v[62:65]
	v_mfma_f32_16x16x32_bf16 v[58:61], v[138:141], v[162:165], v[58:61]
	v_mfma_f32_16x16x32_bf16 v[50:53], v[130:133], v[170:173], v[50:53]
	v_mfma_f32_16x16x32_bf16 v[42:45], v[138:141], v[170:173], v[42:45]
	v_mfma_f32_16x16x32_bf16 v[34:37], v[130:133], v[178:181], v[34:37]
	v_mfma_f32_16x16x32_bf16 v[26:29], v[138:141], v[178:181], v[26:29]
	v_mfma_f32_16x16x32_bf16 v[18:21], v[130:133], v[196:199], v[18:21]
	v_mfma_f32_16x16x32_bf16 v[8:11], v[138:141], v[196:199], v[8:11]
	v_mfma_f32_16x16x32_bf16 v[62:65], v[134:137], v[166:169], v[62:65]
	v_mfma_f32_16x16x32_bf16 v[58:61], v[142:145], v[166:169], v[58:61]
	v_mfma_f32_16x16x32_bf16 v[50:53], v[134:137], v[174:177], v[50:53]
	v_mfma_f32_16x16x32_bf16 v[42:45], v[142:145], v[174:177], v[42:45]
	v_mfma_f32_16x16x32_bf16 v[34:37], v[134:137], v[192:195], v[34:37]
	v_mfma_f32_16x16x32_bf16 v[26:29], v[142:145], v[192:195], v[26:29]
	v_mfma_f32_16x16x32_bf16 v[18:21], v[134:137], v[224:227], v[18:21]
	v_mfma_f32_16x16x32_bf16 v[8:11], v[142:145], v[224:227], v[8:11]
	s_setprio 0
	s_setprio 1
	v_mfma_f32_16x16x32_bf16 v[54:57], v[146:149], v[162:165], v[54:57]
	v_mfma_f32_16x16x32_bf16 v[46:49], v[154:157], v[162:165], v[46:49]
	v_mfma_f32_16x16x32_bf16 v[38:41], v[146:149], v[170:173], v[38:41]
	v_mfma_f32_16x16x32_bf16 v[30:33], v[154:157], v[170:173], v[30:33]
	v_mfma_f32_16x16x32_bf16 v[22:25], v[146:149], v[178:181], v[22:25]
	v_mfma_f32_16x16x32_bf16 v[12:15], v[154:157], v[178:181], v[12:15]
	v_mfma_f32_16x16x32_bf16 v[4:7], v[146:149], v[196:199], v[4:7]
	v_mfma_f32_16x16x32_bf16 v[0:3], v[154:157], v[196:199], v[0:3]
	v_mfma_f32_16x16x32_bf16 v[54:57], v[150:153], v[166:169], v[54:57]
	v_mfma_f32_16x16x32_bf16 v[46:49], v[158:161], v[166:169], v[46:49]
	v_mfma_f32_16x16x32_bf16 v[38:41], v[150:153], v[174:177], v[38:41]
	v_mfma_f32_16x16x32_bf16 v[30:33], v[158:161], v[174:177], v[30:33]
	v_mfma_f32_16x16x32_bf16 v[22:25], v[150:153], v[192:195], v[22:25]
	v_mfma_f32_16x16x32_bf16 v[12:15], v[158:161], v[192:195], v[12:15]
	v_mfma_f32_16x16x32_bf16 v[4:7], v[150:153], v[224:227], v[4:7]
	v_mfma_f32_16x16x32_bf16 v[0:3], v[158:161], v[224:227], v[0:3]
	s_setprio 0
	s_barrier
	s_add_i32 s86, s86, 2
	s_add_u32 s42, s42, 0x100
	s_addc_u32 s43, s43, 0
	s_cmpk_gt_u32 s86, 0x55
	s_mov_b64 s[26:27], s[36:37]
	s_cbranch_scc1 .Lpz_J_exit
